# ss-hoist + P9 all-WG block scan + packed-f32 swiglu epilogue + attention max canonicalization removed
# speedup vs baseline: 1.0133x; 1.0133x over previous
; __device__ __forceinline__ unsigned pk(float lo, float hi) { return pg8::cvt_pk_bf16(lo, hi); }
;     __device__ __forceinline__ void operator()(const pg8::f32x4 (&acc)[2][2][4][2], const pg8::Unit& u, int wr, int wc, int fr, int fq) const {
;         const int row0 = u.pm * 256 + wr * 64 + fr;
; #pragma unroll
;         for (int ai = 0; ai < 2; ++ai)
; #pragma unroll
;             for (int m = 0; m < 4; ++m) {
;                 const int row = row0 + ai * 128 + m * 16; const float rs = rsqrtf(ss[row] * (1.f / DM) + EPS);
;                 float y[8];
; #pragma unroll
;                 for (int n = 0; n < 2; ++n)
; #pragma unroll
;                     for (int i = 0; i < 4; ++i) { const float g = acc[ai][0][m][n][i] * rs, up = acc[ai][1][m][n][i] * rs; y[4 * n + i] = g * up * __builtin_amdgcn_rcpf(1.f + __expf(-g)); }
;                 u32x4 w; w.x = pk(y[0], y[1]); w.y = pk(y[2], y[3]); w.z = pk(y[4], y[5]); w.w = pk(y[6], y[7]);
;                 *(u32x4*)(act + (size_t)row * DFF + u.pn * 128 + wc * 32 + 8 * fq) = w;
;             }
.LBB0_901:
	v_lshl_add_u32 v182, s68, 8, v152
	v_mov_b32_e32 v181, 0
	v_mov_b32_e32 v180, v182
	v_lshl_add_u64 v[180:181], v[180:181], 2, s[8:9]
	global_load_dword v148, v[180:181], off
	global_load_dword v150, v[180:181], off offset:64
	global_load_dword v158, v[180:181], off offset:128
	global_load_dword v160, v[180:181], off offset:192
	global_load_dword v162, v[180:181], off offset:512
	global_load_dword v164, v[180:181], off offset:576
	global_load_dword v166, v[180:181], off offset:640
	global_load_dword v170, v[180:181], off offset:704
	s_lshl_b32 s98, s69, 8
	v_mul_u32_u24_e32 v183, 0x1600, v182
	v_add3_u32 v183, v183, s98, v138
	v_add_u32_e32 v183, s4, v183
	v_mov_b32_e32 v176, 0xbfb8aa3b
	v_mov_b32_e32 v178, 1.0
	s_waitcnt vmcnt(0)
	v_fmamk_f32 v148, v148, 0x3a800000, v157
	v_fmamk_f32 v150, v150, 0x3a800000, v157
	v_fmamk_f32 v158, v158, 0x3a800000, v157
	v_fmamk_f32 v160, v160, 0x3a800000, v157
	v_fmamk_f32 v162, v162, 0x3a800000, v157
	v_fmamk_f32 v164, v164, 0x3a800000, v157
	v_fmamk_f32 v166, v166, 0x3a800000, v157
	v_fmamk_f32 v170, v170, 0x3a800000, v157
	v_mul_f32_e32 v185, 0x4b800000, v148
	v_cmp_gt_f32_e32 vcc, s76, v148
	s_nop 1
	v_cndmask_b32_e32 v148, v148, v185, vcc
	v_rsq_f32_e32 v148, v148
	s_nop 0
	v_mul_f32_e32 v185, 0x45800000, v148
	v_cndmask_b32_e32 v148, v148, v185, vcc
	v_mul_f32_e32 v185, 0x4b800000, v150
	v_cmp_gt_f32_e32 vcc, s76, v150
	s_nop 1
	v_cndmask_b32_e32 v150, v150, v185, vcc
	v_rsq_f32_e32 v150, v150
	s_nop 0
	v_mul_f32_e32 v185, 0x45800000, v150
	v_cndmask_b32_e32 v150, v150, v185, vcc
	v_mul_f32_e32 v185, 0x4b800000, v158
	v_cmp_gt_f32_e32 vcc, s76, v158
	s_nop 1
	v_cndmask_b32_e32 v158, v158, v185, vcc
	v_rsq_f32_e32 v158, v158
	s_nop 0
	v_mul_f32_e32 v185, 0x45800000, v158
	v_cndmask_b32_e32 v158, v158, v185, vcc
	v_mul_f32_e32 v185, 0x4b800000, v160
	v_cmp_gt_f32_e32 vcc, s76, v160
	s_nop 1
	v_cndmask_b32_e32 v160, v160, v185, vcc
	v_rsq_f32_e32 v160, v160
	s_nop 0
	v_mul_f32_e32 v185, 0x45800000, v160
	v_cndmask_b32_e32 v160, v160, v185, vcc
	v_mul_f32_e32 v185, 0x4b800000, v162
	v_cmp_gt_f32_e32 vcc, s76, v162
	s_nop 1
	v_cndmask_b32_e32 v162, v162, v185, vcc
	v_rsq_f32_e32 v162, v162
	s_nop 0
	v_mul_f32_e32 v185, 0x45800000, v162
	v_cndmask_b32_e32 v162, v162, v185, vcc
	v_mul_f32_e32 v185, 0x4b800000, v164
	v_cmp_gt_f32_e32 vcc, s76, v164
	s_nop 1
	v_cndmask_b32_e32 v164, v164, v185, vcc
	v_rsq_f32_e32 v164, v164
	s_nop 0
	v_mul_f32_e32 v185, 0x45800000, v164
	v_cndmask_b32_e32 v164, v164, v185, vcc
	v_mul_f32_e32 v185, 0x4b800000, v166
	v_cmp_gt_f32_e32 vcc, s76, v166
	s_nop 1
	v_cndmask_b32_e32 v166, v166, v185, vcc
	v_rsq_f32_e32 v166, v166
	s_nop 0
	v_mul_f32_e32 v185, 0x45800000, v166
	v_cndmask_b32_e32 v166, v166, v185, vcc
	v_mul_f32_e32 v185, 0x4b800000, v170
	v_cmp_gt_f32_e32 vcc, s76, v170
	s_nop 1
	v_cndmask_b32_e32 v170, v170, v185, vcc
	v_rsq_f32_e32 v170, v170
	s_nop 0
	v_mul_f32_e32 v185, 0x45800000, v170
	v_cndmask_b32_e32 v170, v170, v185, vcc
	v_pk_mul_f32 v[126:127], v[126:127], v[148:149] op_sel_hi:[1,0]
	v_pk_mul_f32 v[128:129], v[128:129], v[148:149] op_sel_hi:[1,0]
	v_pk_mul_f32 v[122:123], v[122:123], v[148:149] op_sel_hi:[1,0]
	v_pk_mul_f32 v[124:125], v[124:125], v[148:149] op_sel_hi:[1,0]
	v_pk_mul_f32 v[118:119], v[118:119], v[148:149] op_sel_hi:[1,0]
	v_pk_mul_f32 v[120:121], v[120:121], v[148:149] op_sel_hi:[1,0]
	v_pk_mul_f32 v[114:115], v[114:115], v[148:149] op_sel_hi:[1,0]
	v_pk_mul_f32 v[116:117], v[116:117], v[148:149] op_sel_hi:[1,0]
	v_pk_mul_f32 v[118:119], v[126:127], v[118:119]
	v_pk_mul_f32 v[120:121], v[128:129], v[120:121]
	v_pk_mul_f32 v[114:115], v[122:123], v[114:115]
	v_pk_mul_f32 v[116:117], v[124:125], v[116:117]
	v_pk_mul_f32 v[126:127], v[126:127], v[176:177] op_sel_hi:[1,0]
	v_pk_mul_f32 v[128:129], v[128:129], v[176:177] op_sel_hi:[1,0]
	v_pk_mul_f32 v[122:123], v[122:123], v[176:177] op_sel_hi:[1,0]
	v_pk_mul_f32 v[124:125], v[124:125], v[176:177] op_sel_hi:[1,0]
	v_exp_f32_e32 v126, v126
	v_exp_f32_e32 v127, v127
	v_exp_f32_e32 v128, v128
	v_exp_f32_e32 v129, v129
	v_exp_f32_e32 v122, v122
	v_exp_f32_e32 v123, v123
	v_exp_f32_e32 v124, v124
	v_exp_f32_e32 v125, v125
	v_pk_add_f32 v[126:127], v[126:127], v[178:179] op_sel_hi:[1,0]
	v_pk_add_f32 v[128:129], v[128:129], v[178:179] op_sel_hi:[1,0]
	v_pk_add_f32 v[122:123], v[122:123], v[178:179] op_sel_hi:[1,0]
	v_pk_add_f32 v[124:125], v[124:125], v[178:179] op_sel_hi:[1,0]
	v_rcp_f32_e32 v126, v126
	v_rcp_f32_e32 v127, v127
	v_rcp_f32_e32 v128, v128
	v_rcp_f32_e32 v129, v129
	v_rcp_f32_e32 v122, v122
	v_rcp_f32_e32 v123, v123
	v_rcp_f32_e32 v124, v124
	v_rcp_f32_e32 v125, v125
	v_pk_mul_f32 v[118:119], v[118:119], v[126:127]
	v_pk_mul_f32 v[120:121], v[120:121], v[128:129]
	v_pk_mul_f32 v[114:115], v[114:115], v[122:123]
	v_pk_mul_f32 v[116:117], v[116:117], v[124:125]
	v_cvt_pk_bf16_f32 v172, v118, v119
	v_cvt_pk_bf16_f32 v173, v120, v121
	v_cvt_pk_bf16_f32 v174, v114, v115
	v_cvt_pk_bf16_f32 v175, v116, v117
	global_store_dwordx4 v183, v[172:175], s[12:13]
	s_nop 1
	v_pk_mul_f32 v[110:111], v[110:111], v[150:151] op_sel_hi:[1,0]
	v_pk_mul_f32 v[112:113], v[112:113], v[150:151] op_sel_hi:[1,0]
	v_pk_mul_f32 v[106:107], v[106:107], v[150:151] op_sel_hi:[1,0]
	v_pk_mul_f32 v[108:109], v[108:109], v[150:151] op_sel_hi:[1,0]
	v_pk_mul_f32 v[102:103], v[102:103], v[150:151] op_sel_hi:[1,0]
	v_pk_mul_f32 v[104:105], v[104:105], v[150:151] op_sel_hi:[1,0]
	v_pk_mul_f32 v[98:99], v[98:99], v[150:151] op_sel_hi:[1,0]
	v_pk_mul_f32 v[100:101], v[100:101], v[150:151] op_sel_hi:[1,0]
	v_pk_mul_f32 v[102:103], v[110:111], v[102:103]
	v_pk_mul_f32 v[104:105], v[112:113], v[104:105]
; __device__ __forceinline__ unsigned pk(float lo, float hi) { return pg8::cvt_pk_bf16(lo, hi); }
;     __device__ __forceinline__ void operator()(const pg8::f32x4 (&acc)[2][2][4][2], const pg8::Unit& u, int wr, int wc, int fr, int fq) const {
;     ...
;             for (int m = 0; m < 4; ++m) {
;                 const int row = row0 + ai * 128 + m * 16; const float rs = rsqrtf(ss[row] * (1.f / DM) + EPS);
;                 float y[8];
; #pragma unroll
;                 for (int n = 0; n < 2; ++n)
; #pragma unroll
;                     for (int i = 0; i < 4; ++i) { const float g = acc[ai][0][m][n][i] * rs, up = acc[ai][1][m][n][i] * rs; y[4 * n + i] = g * up * __builtin_amdgcn_rcpf(1.f + __expf(-g)); }
;                 u32x4 w; w.x = pk(y[0], y[1]); w.y = pk(y[2], y[3]); w.z = pk(y[4], y[5]); w.w = pk(y[6], y[7]);
;                 *(u32x4*)(act + (size_t)row * DFF + u.pn * 128 + wc * 32 + 8 * fq) = w;
;             }
	v_pk_mul_f32 v[98:99], v[106:107], v[98:99]
	v_pk_mul_f32 v[100:101], v[108:109], v[100:101]
	v_pk_mul_f32 v[110:111], v[110:111], v[176:177] op_sel_hi:[1,0]
	v_pk_mul_f32 v[112:113], v[112:113], v[176:177] op_sel_hi:[1,0]
	v_pk_mul_f32 v[106:107], v[106:107], v[176:177] op_sel_hi:[1,0]
	v_pk_mul_f32 v[108:109], v[108:109], v[176:177] op_sel_hi:[1,0]
	v_exp_f32_e32 v110, v110
	v_exp_f32_e32 v111, v111
	v_exp_f32_e32 v112, v112
	v_exp_f32_e32 v113, v113
	v_exp_f32_e32 v106, v106
	v_exp_f32_e32 v107, v107
	v_exp_f32_e32 v108, v108
	v_exp_f32_e32 v109, v109
	v_pk_add_f32 v[110:111], v[110:111], v[178:179] op_sel_hi:[1,0]
	v_pk_add_f32 v[112:113], v[112:113], v[178:179] op_sel_hi:[1,0]
	v_pk_add_f32 v[106:107], v[106:107], v[178:179] op_sel_hi:[1,0]
	v_pk_add_f32 v[108:109], v[108:109], v[178:179] op_sel_hi:[1,0]
	v_rcp_f32_e32 v110, v110
	v_rcp_f32_e32 v111, v111
	v_rcp_f32_e32 v112, v112
	v_rcp_f32_e32 v113, v113
	v_rcp_f32_e32 v106, v106
	v_rcp_f32_e32 v107, v107
	v_rcp_f32_e32 v108, v108
	v_rcp_f32_e32 v109, v109
	v_pk_mul_f32 v[102:103], v[102:103], v[110:111]
	v_pk_mul_f32 v[104:105], v[104:105], v[112:113]
	v_pk_mul_f32 v[98:99], v[98:99], v[106:107]
	v_pk_mul_f32 v[100:101], v[100:101], v[108:109]
	v_cvt_pk_bf16_f32 v172, v102, v103
	v_cvt_pk_bf16_f32 v173, v104, v105
	v_cvt_pk_bf16_f32 v174, v98, v99
	v_cvt_pk_bf16_f32 v175, v100, v101
	v_add_u32_e32 v184, 0x16000, v183
	global_store_dwordx4 v184, v[172:175], s[12:13]
	s_nop 1
	v_pk_mul_f32 v[94:95], v[94:95], v[158:159] op_sel_hi:[1,0]
	v_pk_mul_f32 v[96:97], v[96:97], v[158:159] op_sel_hi:[1,0]
	v_pk_mul_f32 v[90:91], v[90:91], v[158:159] op_sel_hi:[1,0]
	v_pk_mul_f32 v[92:93], v[92:93], v[158:159] op_sel_hi:[1,0]
	v_pk_mul_f32 v[86:87], v[86:87], v[158:159] op_sel_hi:[1,0]
	v_pk_mul_f32 v[88:89], v[88:89], v[158:159] op_sel_hi:[1,0]
	v_pk_mul_f32 v[82:83], v[82:83], v[158:159] op_sel_hi:[1,0]
	v_pk_mul_f32 v[84:85], v[84:85], v[158:159] op_sel_hi:[1,0]
	v_pk_mul_f32 v[86:87], v[94:95], v[86:87]
	v_pk_mul_f32 v[88:89], v[96:97], v[88:89]
	v_pk_mul_f32 v[82:83], v[90:91], v[82:83]
	v_pk_mul_f32 v[84:85], v[92:93], v[84:85]
	v_pk_mul_f32 v[94:95], v[94:95], v[176:177] op_sel_hi:[1,0]
	v_pk_mul_f32 v[96:97], v[96:97], v[176:177] op_sel_hi:[1,0]
	v_pk_mul_f32 v[90:91], v[90:91], v[176:177] op_sel_hi:[1,0]
	v_pk_mul_f32 v[92:93], v[92:93], v[176:177] op_sel_hi:[1,0]
	v_exp_f32_e32 v94, v94
	v_exp_f32_e32 v95, v95
	v_exp_f32_e32 v96, v96
	v_exp_f32_e32 v97, v97
	v_exp_f32_e32 v90, v90
	v_exp_f32_e32 v91, v91
	v_exp_f32_e32 v92, v92
	v_exp_f32_e32 v93, v93
	v_pk_add_f32 v[94:95], v[94:95], v[178:179] op_sel_hi:[1,0]
	v_pk_add_f32 v[96:97], v[96:97], v[178:179] op_sel_hi:[1,0]
	v_pk_add_f32 v[90:91], v[90:91], v[178:179] op_sel_hi:[1,0]
	v_pk_add_f32 v[92:93], v[92:93], v[178:179] op_sel_hi:[1,0]
	v_rcp_f32_e32 v94, v94
	v_rcp_f32_e32 v95, v95
	v_rcp_f32_e32 v96, v96
	v_rcp_f32_e32 v97, v97
	v_rcp_f32_e32 v90, v90
	v_rcp_f32_e32 v91, v91
	v_rcp_f32_e32 v92, v92
	v_rcp_f32_e32 v93, v93
	v_pk_mul_f32 v[86:87], v[86:87], v[94:95]
	v_pk_mul_f32 v[88:89], v[88:89], v[96:97]
	v_pk_mul_f32 v[82:83], v[82:83], v[90:91]
	v_pk_mul_f32 v[84:85], v[84:85], v[92:93]
	v_cvt_pk_bf16_f32 v172, v86, v87
	v_cvt_pk_bf16_f32 v173, v88, v89
	v_cvt_pk_bf16_f32 v174, v82, v83
	v_cvt_pk_bf16_f32 v175, v84, v85
	v_add_u32_e32 v184, 0x2c000, v183
	global_store_dwordx4 v184, v[172:175], s[12:13]
	s_nop 1
	v_pk_mul_f32 v[78:79], v[78:79], v[160:161] op_sel_hi:[1,0]
	v_pk_mul_f32 v[80:81], v[80:81], v[160:161] op_sel_hi:[1,0]
	v_pk_mul_f32 v[74:75], v[74:75], v[160:161] op_sel_hi:[1,0]
	v_pk_mul_f32 v[76:77], v[76:77], v[160:161] op_sel_hi:[1,0]
	v_pk_mul_f32 v[70:71], v[70:71], v[160:161] op_sel_hi:[1,0]
	v_pk_mul_f32 v[72:73], v[72:73], v[160:161] op_sel_hi:[1,0]
	v_pk_mul_f32 v[66:67], v[66:67], v[160:161] op_sel_hi:[1,0]
	v_pk_mul_f32 v[68:69], v[68:69], v[160:161] op_sel_hi:[1,0]
	v_pk_mul_f32 v[70:71], v[78:79], v[70:71]
	v_pk_mul_f32 v[72:73], v[80:81], v[72:73]
	v_pk_mul_f32 v[66:67], v[74:75], v[66:67]
	v_pk_mul_f32 v[68:69], v[76:77], v[68:69]
	v_pk_mul_f32 v[78:79], v[78:79], v[176:177] op_sel_hi:[1,0]
	v_pk_mul_f32 v[80:81], v[80:81], v[176:177] op_sel_hi:[1,0]
	v_pk_mul_f32 v[74:75], v[74:75], v[176:177] op_sel_hi:[1,0]
	v_pk_mul_f32 v[76:77], v[76:77], v[176:177] op_sel_hi:[1,0]
	v_exp_f32_e32 v78, v78
	v_exp_f32_e32 v79, v79
	v_exp_f32_e32 v80, v80
	v_exp_f32_e32 v81, v81
	v_exp_f32_e32 v74, v74
	v_exp_f32_e32 v75, v75
	v_exp_f32_e32 v76, v76
	v_exp_f32_e32 v77, v77
	v_pk_add_f32 v[78:79], v[78:79], v[178:179] op_sel_hi:[1,0]
	v_pk_add_f32 v[80:81], v[80:81], v[178:179] op_sel_hi:[1,0]
	v_pk_add_f32 v[74:75], v[74:75], v[178:179] op_sel_hi:[1,0]
	v_pk_add_f32 v[76:77], v[76:77], v[178:179] op_sel_hi:[1,0]
	v_rcp_f32_e32 v78, v78
	v_rcp_f32_e32 v79, v79
	v_rcp_f32_e32 v80, v80
	v_rcp_f32_e32 v81, v81
	v_rcp_f32_e32 v74, v74
	v_rcp_f32_e32 v75, v75
	v_rcp_f32_e32 v76, v76
	v_rcp_f32_e32 v77, v77
	v_pk_mul_f32 v[70:71], v[70:71], v[78:79]
	v_pk_mul_f32 v[72:73], v[72:73], v[80:81]
	v_pk_mul_f32 v[66:67], v[66:67], v[74:75]
	v_pk_mul_f32 v[68:69], v[68:69], v[76:77]
	v_cvt_pk_bf16_f32 v172, v70, v71
	v_cvt_pk_bf16_f32 v173, v72, v73
	v_cvt_pk_bf16_f32 v174, v66, v67
	v_cvt_pk_bf16_f32 v175, v68, v69
	v_add_u32_e32 v184, 0x42000, v183
	global_store_dwordx4 v184, v[172:175], s[12:13]
	s_nop 1
	v_pk_mul_f32 v[62:63], v[62:63], v[162:163] op_sel_hi:[1,0]
	v_pk_mul_f32 v[64:65], v[64:65], v[162:163] op_sel_hi:[1,0]
	v_pk_mul_f32 v[58:59], v[58:59], v[162:163] op_sel_hi:[1,0]
	v_pk_mul_f32 v[60:61], v[60:61], v[162:163] op_sel_hi:[1,0]
	v_pk_mul_f32 v[54:55], v[54:55], v[162:163] op_sel_hi:[1,0]
; __device__ __forceinline__ unsigned pk(float lo, float hi) { return pg8::cvt_pk_bf16(lo, hi); }
;     __device__ __forceinline__ void operator()(const pg8::f32x4 (&acc)[2][2][4][2], const pg8::Unit& u, int wr, int wc, int fr, int fq) const {
;     ...
;             for (int m = 0; m < 4; ++m) {
;                 const int row = row0 + ai * 128 + m * 16; const float rs = rsqrtf(ss[row] * (1.f / DM) + EPS);
;                 float y[8];
; #pragma unroll
;                 for (int n = 0; n < 2; ++n)
; #pragma unroll
;                     for (int i = 0; i < 4; ++i) { const float g = acc[ai][0][m][n][i] * rs, up = acc[ai][1][m][n][i] * rs; y[4 * n + i] = g * up * __builtin_amdgcn_rcpf(1.f + __expf(-g)); }
;                 u32x4 w; w.x = pk(y[0], y[1]); w.y = pk(y[2], y[3]); w.z = pk(y[4], y[5]); w.w = pk(y[6], y[7]);
;                 *(u32x4*)(act + (size_t)row * DFF + u.pn * 128 + wc * 32 + 8 * fq) = w;
;             }
	v_pk_mul_f32 v[56:57], v[56:57], v[162:163] op_sel_hi:[1,0]
	v_pk_mul_f32 v[50:51], v[50:51], v[162:163] op_sel_hi:[1,0]
	v_pk_mul_f32 v[52:53], v[52:53], v[162:163] op_sel_hi:[1,0]
	v_pk_mul_f32 v[54:55], v[62:63], v[54:55]
	v_pk_mul_f32 v[56:57], v[64:65], v[56:57]
	v_pk_mul_f32 v[50:51], v[58:59], v[50:51]
	v_pk_mul_f32 v[52:53], v[60:61], v[52:53]
	v_pk_mul_f32 v[62:63], v[62:63], v[176:177] op_sel_hi:[1,0]
	v_pk_mul_f32 v[64:65], v[64:65], v[176:177] op_sel_hi:[1,0]
	v_pk_mul_f32 v[58:59], v[58:59], v[176:177] op_sel_hi:[1,0]
	v_pk_mul_f32 v[60:61], v[60:61], v[176:177] op_sel_hi:[1,0]
	v_exp_f32_e32 v62, v62
	v_exp_f32_e32 v63, v63
	v_exp_f32_e32 v64, v64
	v_exp_f32_e32 v65, v65
	v_exp_f32_e32 v58, v58
	v_exp_f32_e32 v59, v59
	v_exp_f32_e32 v60, v60
	v_exp_f32_e32 v61, v61
	v_pk_add_f32 v[62:63], v[62:63], v[178:179] op_sel_hi:[1,0]
	v_pk_add_f32 v[64:65], v[64:65], v[178:179] op_sel_hi:[1,0]
	v_pk_add_f32 v[58:59], v[58:59], v[178:179] op_sel_hi:[1,0]
	v_pk_add_f32 v[60:61], v[60:61], v[178:179] op_sel_hi:[1,0]
	v_rcp_f32_e32 v62, v62
	v_rcp_f32_e32 v63, v63
	v_rcp_f32_e32 v64, v64
	v_rcp_f32_e32 v65, v65
	v_rcp_f32_e32 v58, v58
	v_rcp_f32_e32 v59, v59
	v_rcp_f32_e32 v60, v60
	v_rcp_f32_e32 v61, v61
	v_pk_mul_f32 v[54:55], v[54:55], v[62:63]
	v_pk_mul_f32 v[56:57], v[56:57], v[64:65]
	v_pk_mul_f32 v[50:51], v[50:51], v[58:59]
	v_pk_mul_f32 v[52:53], v[52:53], v[60:61]
	v_cvt_pk_bf16_f32 v172, v54, v55
	v_cvt_pk_bf16_f32 v173, v56, v57
	v_cvt_pk_bf16_f32 v174, v50, v51
	v_cvt_pk_bf16_f32 v175, v52, v53
	v_add_u32_e32 v184, 0xb0000, v183
	global_store_dwordx4 v184, v[172:175], s[12:13]
	s_nop 1
	v_pk_mul_f32 v[46:47], v[46:47], v[164:165] op_sel_hi:[1,0]
	v_pk_mul_f32 v[48:49], v[48:49], v[164:165] op_sel_hi:[1,0]
	v_pk_mul_f32 v[42:43], v[42:43], v[164:165] op_sel_hi:[1,0]
	v_pk_mul_f32 v[44:45], v[44:45], v[164:165] op_sel_hi:[1,0]
	v_pk_mul_f32 v[38:39], v[38:39], v[164:165] op_sel_hi:[1,0]
	v_pk_mul_f32 v[40:41], v[40:41], v[164:165] op_sel_hi:[1,0]
	v_pk_mul_f32 v[34:35], v[34:35], v[164:165] op_sel_hi:[1,0]
	v_pk_mul_f32 v[36:37], v[36:37], v[164:165] op_sel_hi:[1,0]
	v_pk_mul_f32 v[38:39], v[46:47], v[38:39]
	v_pk_mul_f32 v[40:41], v[48:49], v[40:41]
	v_pk_mul_f32 v[34:35], v[42:43], v[34:35]
	v_pk_mul_f32 v[36:37], v[44:45], v[36:37]
	v_pk_mul_f32 v[46:47], v[46:47], v[176:177] op_sel_hi:[1,0]
	v_pk_mul_f32 v[48:49], v[48:49], v[176:177] op_sel_hi:[1,0]
	v_pk_mul_f32 v[42:43], v[42:43], v[176:177] op_sel_hi:[1,0]
	v_pk_mul_f32 v[44:45], v[44:45], v[176:177] op_sel_hi:[1,0]
	v_exp_f32_e32 v46, v46
	v_exp_f32_e32 v47, v47
	v_exp_f32_e32 v48, v48
	v_exp_f32_e32 v49, v49
	v_exp_f32_e32 v42, v42
	v_exp_f32_e32 v43, v43
	v_exp_f32_e32 v44, v44
	v_exp_f32_e32 v45, v45
	v_pk_add_f32 v[46:47], v[46:47], v[178:179] op_sel_hi:[1,0]
	v_pk_add_f32 v[48:49], v[48:49], v[178:179] op_sel_hi:[1,0]
	v_pk_add_f32 v[42:43], v[42:43], v[178:179] op_sel_hi:[1,0]
	v_pk_add_f32 v[44:45], v[44:45], v[178:179] op_sel_hi:[1,0]
	v_rcp_f32_e32 v46, v46
	v_rcp_f32_e32 v47, v47
	v_rcp_f32_e32 v48, v48
	v_rcp_f32_e32 v49, v49
	v_rcp_f32_e32 v42, v42
	v_rcp_f32_e32 v43, v43
	v_rcp_f32_e32 v44, v44
	v_rcp_f32_e32 v45, v45
	v_pk_mul_f32 v[38:39], v[38:39], v[46:47]
	v_pk_mul_f32 v[40:41], v[40:41], v[48:49]
	v_pk_mul_f32 v[34:35], v[34:35], v[42:43]
	v_pk_mul_f32 v[36:37], v[36:37], v[44:45]
	v_cvt_pk_bf16_f32 v172, v38, v39
	v_cvt_pk_bf16_f32 v173, v40, v41
	v_cvt_pk_bf16_f32 v174, v34, v35
	v_cvt_pk_bf16_f32 v175, v36, v37
	v_add_u32_e32 v184, 0xc6000, v183
	global_store_dwordx4 v184, v[172:175], s[12:13]
	s_nop 1
	v_pk_mul_f32 v[30:31], v[30:31], v[166:167] op_sel_hi:[1,0]
	v_pk_mul_f32 v[32:33], v[32:33], v[166:167] op_sel_hi:[1,0]
	v_pk_mul_f32 v[26:27], v[26:27], v[166:167] op_sel_hi:[1,0]
; #define PG8_BAR __builtin_amdgcn_s_barrier()
; __device__ __forceinline__ unsigned pk(float lo, float hi) { return pg8::cvt_pk_bf16(lo, hi); }
; template <class Epi, class Sched, bool ALIGN_EPI = false, bool SP2 = false>
; __device__ __forceinline__ void gemm_phase(PG8_LAS unsigned char* lds, const Gemm g, const Sched& S, const Epi& E) {
;     ...
;         if (!has_next) break;
; #pragma unroll
;         for (int a = 0; a < 2; ++a)
; #pragma unroll
;             for (int b = 0; b < 2; ++b)
; #pragma unroll
;                 for (int m = 0; m < 4; ++m)
; #pragma unroll
;                     for (int n = 0; n < 2; ++n) acc[a][b][m][n] = (f32x4){0.f, 0.f, 0.f, 0.f};
;         cur = nxt; cA = nA; cB = nB; ++ui;
;         if constexpr (ALIGN_EPI) { if (wr == 1) PG8_BAR; }
;     __device__ __forceinline__ void operator()(const pg8::f32x4 (&acc)[2][2][4][2], const pg8::Unit& u, int wr, int wc, int fr, int fq) const {
;     ...
;             for (int m = 0; m < 4; ++m) {
;                 const int row = row0 + ai * 128 + m * 16; const float rs = rsqrtf(ss[row] * (1.f / DM) + EPS);
;                 float y[8];
; #pragma unroll
;                 for (int n = 0; n < 2; ++n)
; #pragma unroll
;                     for (int i = 0; i < 4; ++i) { const float g = acc[ai][0][m][n][i] * rs, up = acc[ai][1][m][n][i] * rs; y[4 * n + i] = g * up * __builtin_amdgcn_rcpf(1.f + __expf(-g)); }
;                 u32x4 w; w.x = pk(y[0], y[1]); w.y = pk(y[2], y[3]); w.z = pk(y[4], y[5]); w.w = pk(y[6], y[7]);
;                 *(u32x4*)(act + (size_t)row * DFF + u.pn * 128 + wc * 32 + 8 * fq) = w;
;             }
	v_pk_mul_f32 v[28:29], v[28:29], v[166:167] op_sel_hi:[1,0]
	v_pk_mul_f32 v[22:23], v[22:23], v[166:167] op_sel_hi:[1,0]
	v_pk_mul_f32 v[24:25], v[24:25], v[166:167] op_sel_hi:[1,0]
	v_pk_mul_f32 v[18:19], v[18:19], v[166:167] op_sel_hi:[1,0]
	v_pk_mul_f32 v[20:21], v[20:21], v[166:167] op_sel_hi:[1,0]
	v_pk_mul_f32 v[22:23], v[30:31], v[22:23]
	v_pk_mul_f32 v[24:25], v[32:33], v[24:25]
	v_pk_mul_f32 v[18:19], v[26:27], v[18:19]
	v_pk_mul_f32 v[20:21], v[28:29], v[20:21]
	v_pk_mul_f32 v[30:31], v[30:31], v[176:177] op_sel_hi:[1,0]
	v_pk_mul_f32 v[32:33], v[32:33], v[176:177] op_sel_hi:[1,0]
	v_pk_mul_f32 v[26:27], v[26:27], v[176:177] op_sel_hi:[1,0]
	v_pk_mul_f32 v[28:29], v[28:29], v[176:177] op_sel_hi:[1,0]
	v_exp_f32_e32 v30, v30
	v_exp_f32_e32 v31, v31
	v_exp_f32_e32 v32, v32
	v_exp_f32_e32 v33, v33
	v_exp_f32_e32 v26, v26
	v_exp_f32_e32 v27, v27
	v_exp_f32_e32 v28, v28
	v_exp_f32_e32 v29, v29
	v_pk_add_f32 v[30:31], v[30:31], v[178:179] op_sel_hi:[1,0]
	v_pk_add_f32 v[32:33], v[32:33], v[178:179] op_sel_hi:[1,0]
	v_pk_add_f32 v[26:27], v[26:27], v[178:179] op_sel_hi:[1,0]
	v_pk_add_f32 v[28:29], v[28:29], v[178:179] op_sel_hi:[1,0]
	v_rcp_f32_e32 v30, v30
	v_rcp_f32_e32 v31, v31
	v_rcp_f32_e32 v32, v32
	v_rcp_f32_e32 v33, v33
	v_rcp_f32_e32 v26, v26
	v_rcp_f32_e32 v27, v27
	v_rcp_f32_e32 v28, v28
	v_rcp_f32_e32 v29, v29
	v_pk_mul_f32 v[22:23], v[22:23], v[30:31]
	v_pk_mul_f32 v[24:25], v[24:25], v[32:33]
	v_pk_mul_f32 v[18:19], v[18:19], v[26:27]
	v_pk_mul_f32 v[20:21], v[20:21], v[28:29]
	v_cvt_pk_bf16_f32 v172, v22, v23
	v_cvt_pk_bf16_f32 v173, v24, v25
	v_cvt_pk_bf16_f32 v174, v18, v19
	v_cvt_pk_bf16_f32 v175, v20, v21
	v_add_u32_e32 v184, 0xdc000, v183
	global_store_dwordx4 v184, v[172:175], s[12:13]
	s_nop 1
	v_pk_mul_f32 v[14:15], v[14:15], v[170:171] op_sel_hi:[1,0]
	v_pk_mul_f32 v[16:17], v[16:17], v[170:171] op_sel_hi:[1,0]
	v_pk_mul_f32 v[10:11], v[10:11], v[170:171] op_sel_hi:[1,0]
	v_pk_mul_f32 v[12:13], v[12:13], v[170:171] op_sel_hi:[1,0]
	v_pk_mul_f32 v[6:7], v[6:7], v[170:171] op_sel_hi:[1,0]
	v_pk_mul_f32 v[8:9], v[8:9], v[170:171] op_sel_hi:[1,0]
	v_pk_mul_f32 v[2:3], v[2:3], v[170:171] op_sel_hi:[1,0]
	v_pk_mul_f32 v[4:5], v[4:5], v[170:171] op_sel_hi:[1,0]
	v_pk_mul_f32 v[6:7], v[14:15], v[6:7]
	v_pk_mul_f32 v[8:9], v[16:17], v[8:9]
	v_pk_mul_f32 v[2:3], v[10:11], v[2:3]
	v_pk_mul_f32 v[4:5], v[12:13], v[4:5]
	v_pk_mul_f32 v[14:15], v[14:15], v[176:177] op_sel_hi:[1,0]
	v_pk_mul_f32 v[16:17], v[16:17], v[176:177] op_sel_hi:[1,0]
	v_pk_mul_f32 v[10:11], v[10:11], v[176:177] op_sel_hi:[1,0]
	v_pk_mul_f32 v[12:13], v[12:13], v[176:177] op_sel_hi:[1,0]
	v_exp_f32_e32 v14, v14
	v_exp_f32_e32 v15, v15
	v_exp_f32_e32 v16, v16
	v_exp_f32_e32 v17, v17
	v_exp_f32_e32 v10, v10
	v_exp_f32_e32 v11, v11
	v_exp_f32_e32 v12, v12
	v_exp_f32_e32 v13, v13
	v_pk_add_f32 v[14:15], v[14:15], v[178:179] op_sel_hi:[1,0]
	v_pk_add_f32 v[16:17], v[16:17], v[178:179] op_sel_hi:[1,0]
	v_pk_add_f32 v[10:11], v[10:11], v[178:179] op_sel_hi:[1,0]
	v_pk_add_f32 v[12:13], v[12:13], v[178:179] op_sel_hi:[1,0]
	v_rcp_f32_e32 v14, v14
	v_rcp_f32_e32 v15, v15
	v_rcp_f32_e32 v16, v16
	v_rcp_f32_e32 v17, v17
	v_rcp_f32_e32 v10, v10
	v_rcp_f32_e32 v11, v11
	v_rcp_f32_e32 v12, v12
	v_rcp_f32_e32 v13, v13
	v_pk_mul_f32 v[6:7], v[6:7], v[14:15]
	v_pk_mul_f32 v[8:9], v[8:9], v[16:17]
	v_pk_mul_f32 v[2:3], v[2:3], v[10:11]
	v_pk_mul_f32 v[4:5], v[4:5], v[12:13]
	v_cvt_pk_bf16_f32 v172, v6, v7
	v_cvt_pk_bf16_f32 v173, v8, v9
	v_cvt_pk_bf16_f32 v174, v2, v3
	v_cvt_pk_bf16_f32 v175, v4, v5
	v_add_u32_e32 v184, 0xf2000, v183
	global_store_dwordx4 v184, v[172:175], s[12:13]
	s_nop 1
	s_andn2_b64 vcc, exec, s[0:1]
	s_mov_b64 s[0:1], -1
	s_cbranch_vccnz .LBB0_894
	s_andn2_b64 vcc, exec, s[6:7]
	s_cbranch_vccnz .LBB0_893
	s_barrier
	s_branch .LBB0_893

; template <bool QLDS> __device__ __forceinline__ void attn_tile(const LAS unsigned char* buf, const bf16x8 (&qf)[4], const LAS bf16x8* qlds, float cq2, int qpos, int kv0, bool diag, float& mrun, float& lrun, f32x16 (&ot)[2], int l31, int hi) {
;     ...
;     float rm = fmaxf(p0[0], p1[0]);
; #pragma unroll
;     for (int r = 1; r < 16; ++r) rm = fmaxf(rm, fmaxf(p0[r], p1[r]));
;     rm = fmaxf(rm, __shfl_xor(rm, 32));
;     if (__all(rm < mrun - 40.f)) return;
;     const float mn = fmaxf(mrun, rm);
;     if (__any(mn > mrun)) {
.LBB0_1654:
	s_nop 10
	v_max_f32_e32 v66, v69, v51
	v_max_f32_e32 v147, v70, v52
	v_max3_f32 v66, v68, v50, v66
	v_max_f32_e32 v151, v71, v53
	v_max3_f32 v66, v66, v147, v151
	v_max_f32_e32 v147, v72, v54
	v_max_f32_e32 v151, v73, v55
	v_max3_f32 v66, v66, v147, v151
	v_max_f32_e32 v147, v74, v56
	v_max_f32_e32 v151, v75, v57
	v_max3_f32 v66, v66, v147, v151
	v_max_f32_e32 v147, v76, v58
	v_max_f32_e32 v151, v77, v59
	v_max3_f32 v66, v66, v147, v151
	v_max_f32_e32 v147, v78, v60
	v_max_f32_e32 v151, v79, v61
	v_max3_f32 v66, v66, v147, v151
	v_max_f32_e32 v147, v80, v62
	v_max_f32_e32 v151, v81, v63
	v_max3_f32 v66, v66, v147, v151
	v_max_f32_e32 v147, v82, v64
	v_max_f32_e32 v152, v83, v83
	v_max_f32_e32 v151, v152, v65
	v_max3_f32 v66, v66, v147, v151
	v_and_b32_e32 v151, 64, v150
	v_xor_b32_e32 v147, 32, v150
	v_add_u32_e32 v151, 64, v151
	v_cmp_lt_i32_e32 vcc, v147, v151
	s_nop 1
	v_cndmask_b32_e32 v147, v150, v147, vcc
	v_lshlrev_b32_e32 v147, 2, v147
	ds_bpermute_b32 v147, v147, v66
	s_waitcnt lgkmcnt(0)
	v_max_f32_e32 v66, v66, v147
	v_add_f32_e32 v147, 0xc2200000, v146
	v_cmp_lt_f32_e32 vcc, v66, v147
	s_cmp_eq_u64 vcc, exec
	s_cbranch_scc1 .LBB0_1650
	v_max_f32_e32 v147, v146, v146
	v_max_f32_e32 v66, v147, v66
	v_cmp_gt_f32_e32 vcc, v66, v146
	s_cbranch_vccnz .LBB0_1648
	v_mov_b32_e32 v66, v146
	s_branch .LBB0_1649

; template <bool QLDS> __device__ __forceinline__ void attn_tile(const LAS unsigned char* buf, const bf16x8 (&qf)[4], const LAS bf16x8* qlds, float cq2, int qpos, int kv0, bool diag, float& mrun, float& lrun, f32x16 (&ot)[2], int l31, int hi) {
;     ...
;     float rm = fmaxf(p0[0], p1[0]);
; #pragma unroll
;     for (int r = 1; r < 16; ++r) rm = fmaxf(rm, fmaxf(p0[r], p1[r]));
;     rm = fmaxf(rm, __shfl_xor(rm, 32));
;     if (__all(rm < mrun - 40.f)) return;
;     const float mn = fmaxf(mrun, rm);
;     if (__any(mn > mrun)) {
;         const float alpha = __builtin_amdgcn_exp2f(mrun - mn);
;         lrun *= alpha;
; #pragma unroll
;         for (int r = 0; r < 16; ++r) { ot[0][r] *= alpha; ot[1][r] *= alpha; }
;         mrun = mn;
.LBB0_1684:
	s_nop 10
	v_max_f32_e32 v123, v51, v69
	v_max_f32_e32 v203, v52, v70
	v_max3_f32 v123, v50, v68, v123
	v_max_f32_e32 v204, v53, v71
	v_max3_f32 v123, v123, v203, v204
	v_max_f32_e32 v203, v54, v72
	v_max_f32_e32 v204, v55, v73
	v_max3_f32 v123, v123, v203, v204
	v_max_f32_e32 v203, v56, v74
	v_max_f32_e32 v204, v57, v75
	v_max3_f32 v123, v123, v203, v204
	v_max_f32_e32 v203, v58, v76
	v_max_f32_e32 v204, v59, v77
	v_max3_f32 v123, v123, v203, v204
	v_max_f32_e32 v203, v60, v78
	v_max_f32_e32 v204, v61, v79
	v_max3_f32 v123, v123, v203, v204
	v_max_f32_e32 v203, v62, v80
	v_max_f32_e32 v204, v63, v81
	v_max3_f32 v123, v123, v203, v204
	v_max_f32_e32 v203, v64, v82
	v_max_f32_e32 v205, v65, v65
	v_max_f32_e32 v204, v205, v83
	v_max3_f32 v123, v123, v203, v204
	v_and_b32_e32 v204, 64, v150
	v_xor_b32_e32 v203, 32, v150
	v_add_u32_e32 v204, 64, v204
	v_cmp_lt_i32_e32 vcc, v203, v204
	s_nop 1
	v_cndmask_b32_e32 v203, v150, v203, vcc
	v_lshlrev_b32_e32 v203, 2, v203
	ds_bpermute_b32 v203, v203, v123
	s_waitcnt lgkmcnt(0)
	v_max_f32_e32 v123, v123, v203
	v_add_f32_e32 v203, 0xc2200000, v202
	v_cmp_lt_f32_e32 vcc, v123, v203
	s_cmp_eq_u64 vcc, exec
	s_cbranch_scc1 .LBB0_1689
	v_max_f32_e32 v203, v202, v202
	v_max_f32_e32 v123, v203, v123
	v_cmp_gt_f32_e32 vcc, v123, v202
	s_cbranch_vccz .LBB0_1687
	v_sub_f32_e32 v202, v202, v123
	v_exp_f32_e32 v202, v202
	s_nop 0
	v_mul_f32_e32 v201, v201, v202
	v_pk_mul_f32 v[16:17], v[16:17], v[202:203] op_sel_hi:[1,0]
	v_pk_mul_f32 v[14:15], v[14:15], v[202:203] op_sel_hi:[1,0]
	v_pk_mul_f32 v[12:13], v[12:13], v[202:203] op_sel_hi:[1,0]
	v_pk_mul_f32 v[10:11], v[10:11], v[202:203] op_sel_hi:[1,0]
	v_pk_mul_f32 v[8:9], v[8:9], v[202:203] op_sel_hi:[1,0]
	v_pk_mul_f32 v[6:7], v[6:7], v[202:203] op_sel_hi:[1,0]
	v_pk_mul_f32 v[4:5], v[4:5], v[202:203] op_sel_hi:[1,0]
	v_pk_mul_f32 v[2:3], v[2:3], v[202:203] op_sel_hi:[1,0]
	v_pk_mul_f32 v[48:49], v[48:49], v[202:203] op_sel_hi:[1,0]
	v_pk_mul_f32 v[46:47], v[46:47], v[202:203] op_sel_hi:[1,0]
	v_pk_mul_f32 v[44:45], v[44:45], v[202:203] op_sel_hi:[1,0]
	v_pk_mul_f32 v[42:43], v[42:43], v[202:203] op_sel_hi:[1,0]
	v_pk_mul_f32 v[40:41], v[40:41], v[202:203] op_sel_hi:[1,0]
	v_pk_mul_f32 v[38:39], v[38:39], v[202:203] op_sel_hi:[1,0]
	v_pk_mul_f32 v[36:37], v[36:37], v[202:203] op_sel_hi:[1,0]
	v_pk_mul_f32 v[34:35], v[34:35], v[202:203] op_sel_hi:[1,0]
	v_mov_b32_e32 v202, v123
	s_branch .LBB0_1688

; template <bool QLDS> __device__ __forceinline__ void attn_tile(const LAS unsigned char* buf, const bf16x8 (&qf)[4], const LAS bf16x8* qlds, float cq2, int qpos, int kv0, bool diag, float& mrun, float& lrun, f32x16 (&ot)[2], int l31, int hi) {
;     ...
;     float rm = fmaxf(p0[0], p1[0]);
; #pragma unroll
;     for (int r = 1; r < 16; ++r) rm = fmaxf(rm, fmaxf(p0[r], p1[r]));
;     rm = fmaxf(rm, __shfl_xor(rm, 32));
;     if (__all(rm < mrun - 40.f)) return;
;     const float mn = fmaxf(mrun, rm);
;     if (__any(mn > mrun)) {
;         const float alpha = __builtin_amdgcn_exp2f(mrun - mn);
;         lrun *= alpha;
; #pragma unroll
;         for (int r = 0; r < 16; ++r) { ot[0][r] *= alpha; ot[1][r] *= alpha; }
;         mrun = mn;
.LBB0_1695:
	s_nop 10
	v_max_f32_e32 v123, v51, v69
	v_max_f32_e32 v205, v52, v70
	v_max3_f32 v123, v50, v68, v123
	v_max_f32_e32 v206, v53, v71
	v_max3_f32 v123, v123, v205, v206
	v_max_f32_e32 v205, v54, v72
	v_max_f32_e32 v206, v55, v73
	v_max3_f32 v123, v123, v205, v206
	v_max_f32_e32 v205, v56, v74
	v_max_f32_e32 v206, v57, v75
	v_max3_f32 v123, v123, v205, v206
	v_max_f32_e32 v205, v58, v76
	v_max_f32_e32 v206, v59, v77
	v_max3_f32 v123, v123, v205, v206
	v_max_f32_e32 v205, v60, v78
	v_max_f32_e32 v206, v61, v79
	v_max3_f32 v123, v123, v205, v206
	v_max_f32_e32 v205, v62, v80
	v_max_f32_e32 v206, v63, v81
	v_max3_f32 v123, v123, v205, v206
	v_max_f32_e32 v205, v64, v82
	v_max_f32_e32 v207, v65, v65
	v_max_f32_e32 v206, v207, v83
	v_max3_f32 v123, v123, v205, v206
	v_and_b32_e32 v206, 64, v150
	v_xor_b32_e32 v205, 32, v150
	v_add_u32_e32 v206, 64, v206
	v_cmp_lt_i32_e32 vcc, v205, v206
	s_nop 1
	v_cndmask_b32_e32 v205, v150, v205, vcc
	v_lshlrev_b32_e32 v205, 2, v205
	ds_bpermute_b32 v205, v205, v123
	s_waitcnt lgkmcnt(0)
	v_max_f32_e32 v123, v123, v205
	v_add_f32_e32 v205, 0xc2200000, v202
	v_cmp_lt_f32_e32 vcc, v123, v205
	s_cmp_eq_u64 vcc, exec
	s_cbranch_scc1 .LBB0_1700
	v_max_f32_e32 v205, v202, v202
	v_max_f32_e32 v123, v205, v123
	v_cmp_gt_f32_e32 vcc, v123, v202
	s_cbranch_vccz .LBB0_1698
	v_sub_f32_e32 v202, v202, v123
	v_exp_f32_e32 v202, v202
	s_nop 0
	v_mul_f32_e32 v201, v201, v202
	v_pk_mul_f32 v[16:17], v[16:17], v[202:203] op_sel_hi:[1,0]
	v_pk_mul_f32 v[14:15], v[14:15], v[202:203] op_sel_hi:[1,0]
	v_pk_mul_f32 v[12:13], v[12:13], v[202:203] op_sel_hi:[1,0]
	v_pk_mul_f32 v[10:11], v[10:11], v[202:203] op_sel_hi:[1,0]
	v_pk_mul_f32 v[8:9], v[8:9], v[202:203] op_sel_hi:[1,0]
	v_pk_mul_f32 v[6:7], v[6:7], v[202:203] op_sel_hi:[1,0]
	v_pk_mul_f32 v[4:5], v[4:5], v[202:203] op_sel_hi:[1,0]
	v_pk_mul_f32 v[2:3], v[2:3], v[202:203] op_sel_hi:[1,0]
	v_pk_mul_f32 v[48:49], v[48:49], v[202:203] op_sel_hi:[1,0]
	v_pk_mul_f32 v[46:47], v[46:47], v[202:203] op_sel_hi:[1,0]
	v_pk_mul_f32 v[44:45], v[44:45], v[202:203] op_sel_hi:[1,0]
	v_pk_mul_f32 v[42:43], v[42:43], v[202:203] op_sel_hi:[1,0]
	v_pk_mul_f32 v[40:41], v[40:41], v[202:203] op_sel_hi:[1,0]
	v_pk_mul_f32 v[38:39], v[38:39], v[202:203] op_sel_hi:[1,0]
	v_pk_mul_f32 v[36:37], v[36:37], v[202:203] op_sel_hi:[1,0]
	v_pk_mul_f32 v[34:35], v[34:35], v[202:203] op_sel_hi:[1,0]
	v_mov_b32_e32 v202, v123
	s_branch .LBB0_1699

; template <bool QLDS> __device__ __forceinline__ void attn_tile(const LAS unsigned char* buf, const bf16x8 (&qf)[4], const LAS bf16x8* qlds, float cq2, int qpos, int kv0, bool diag, float& mrun, float& lrun, f32x16 (&ot)[2], int l31, int hi) {
;     ...
;     float rm = fmaxf(p0[0], p1[0]);
; #pragma unroll
;     for (int r = 1; r < 16; ++r) rm = fmaxf(rm, fmaxf(p0[r], p1[r]));
;     rm = fmaxf(rm, __shfl_xor(rm, 32));
;     if (__all(rm < mrun - 40.f)) return;
;     const float mn = fmaxf(mrun, rm);
;     if (__any(mn > mrun)) {
;         const float alpha = __builtin_amdgcn_exp2f(mrun - mn);
;         lrun *= alpha;
; #pragma unroll
;         for (int r = 0; r < 16; ++r) { ot[0][r] *= alpha; ot[1][r] *= alpha; }
;         mrun = mn;
.LBB0_1727:
	s_nop 10
	v_max_f32_e32 v129, v69, v85
	v_max_f32_e32 v202, v70, v86
	v_max3_f32 v129, v68, v84, v129
	v_max_f32_e32 v203, v71, v87
	v_max3_f32 v129, v129, v202, v203
	v_max_f32_e32 v202, v72, v88
	v_max_f32_e32 v203, v73, v89
	v_max3_f32 v129, v129, v202, v203
	v_max_f32_e32 v202, v74, v90
	v_max_f32_e32 v203, v75, v91
	v_max3_f32 v129, v129, v202, v203
	v_max_f32_e32 v202, v76, v92
	v_max_f32_e32 v203, v77, v93
	v_max3_f32 v129, v129, v202, v203
	v_max_f32_e32 v202, v78, v94
	v_max_f32_e32 v203, v79, v95
	v_max3_f32 v129, v129, v202, v203
	v_max_f32_e32 v202, v80, v96
	v_max_f32_e32 v203, v81, v97
	v_max3_f32 v129, v129, v202, v203
	v_max_f32_e32 v202, v82, v98
	v_max_f32_e32 v204, v83, v83
	v_max_f32_e32 v203, v204, v99
	v_max3_f32 v129, v129, v202, v203
	v_and_b32_e32 v203, 64, v150
	v_xor_b32_e32 v202, 32, v150
	v_add_u32_e32 v203, 64, v203
	v_cmp_lt_i32_e32 vcc, v202, v203
	s_nop 1
	v_cndmask_b32_e32 v202, v150, v202, vcc
	v_lshlrev_b32_e32 v202, 2, v202
	ds_bpermute_b32 v202, v202, v129
	s_waitcnt lgkmcnt(0)
	v_max_f32_e32 v129, v129, v202
	v_add_f32_e32 v202, 0xc2200000, v201
	v_cmp_lt_f32_e32 vcc, v129, v202
	s_cmp_eq_u64 vcc, exec
	s_cbranch_scc1 .LBB0_1732
	v_max_f32_e32 v202, v201, v201
	v_max_f32_e32 v129, v202, v129
	v_cmp_gt_f32_e32 vcc, v129, v201
	s_cbranch_vccz .LBB0_1730
	v_sub_f32_e32 v201, v201, v129
	v_exp_f32_e32 v202, v201
	v_mov_b32_e32 v201, v129
	v_mul_f32_e32 v34, v34, v202
	v_pk_mul_f32 v[32:33], v[32:33], v[202:203] op_sel_hi:[1,0]
	v_pk_mul_f32 v[30:31], v[30:31], v[202:203] op_sel_hi:[1,0]
	v_pk_mul_f32 v[28:29], v[28:29], v[202:203] op_sel_hi:[1,0]
	v_pk_mul_f32 v[26:27], v[26:27], v[202:203] op_sel_hi:[1,0]
	v_pk_mul_f32 v[24:25], v[24:25], v[202:203] op_sel_hi:[1,0]
	v_pk_mul_f32 v[22:23], v[22:23], v[202:203] op_sel_hi:[1,0]
	v_pk_mul_f32 v[20:21], v[20:21], v[202:203] op_sel_hi:[1,0]
	v_pk_mul_f32 v[18:19], v[18:19], v[202:203] op_sel_hi:[1,0]
	v_pk_mul_f32 v[16:17], v[16:17], v[202:203] op_sel_hi:[1,0]
	v_pk_mul_f32 v[14:15], v[14:15], v[202:203] op_sel_hi:[1,0]
	v_pk_mul_f32 v[12:13], v[12:13], v[202:203] op_sel_hi:[1,0]
	v_pk_mul_f32 v[10:11], v[10:11], v[202:203] op_sel_hi:[1,0]
	v_pk_mul_f32 v[8:9], v[8:9], v[202:203] op_sel_hi:[1,0]
	v_pk_mul_f32 v[6:7], v[6:7], v[202:203] op_sel_hi:[1,0]
	v_pk_mul_f32 v[4:5], v[4:5], v[202:203] op_sel_hi:[1,0]
	v_pk_mul_f32 v[2:3], v[2:3], v[202:203] op_sel_hi:[1,0]
	s_branch .LBB0_1731

; template <bool QLDS> __device__ __forceinline__ void attn_tile(const LAS unsigned char* buf, const bf16x8 (&qf)[4], const LAS bf16x8* qlds, float cq2, int qpos, int kv0, bool diag, float& mrun, float& lrun, f32x16 (&ot)[2], int l31, int hi) {
;     ...
;     float rm = fmaxf(p0[0], p1[0]);
; #pragma unroll
;     for (int r = 1; r < 16; ++r) rm = fmaxf(rm, fmaxf(p0[r], p1[r]));
;     rm = fmaxf(rm, __shfl_xor(rm, 32));
;     if (__all(rm < mrun - 40.f)) return;
;     const float mn = fmaxf(mrun, rm);
;     if (__any(mn > mrun)) {
;         const float alpha = __builtin_amdgcn_exp2f(mrun - mn);
;         lrun *= alpha;
; #pragma unroll
;         for (int r = 0; r < 16; ++r) { ot[0][r] *= alpha; ot[1][r] *= alpha; }
;         mrun = mn;
.LBB0_1738:
	s_nop 10
	v_max_f32_e32 v129, v69, v85
	v_max_f32_e32 v204, v70, v86
	v_max3_f32 v129, v68, v84, v129
	v_max_f32_e32 v205, v71, v87
	v_max3_f32 v129, v129, v204, v205
	v_max_f32_e32 v204, v72, v88
	v_max_f32_e32 v205, v73, v89
	v_max3_f32 v129, v129, v204, v205
	v_max_f32_e32 v204, v74, v90
	v_max_f32_e32 v205, v75, v91
	v_max3_f32 v129, v129, v204, v205
	v_max_f32_e32 v204, v76, v92
	v_max_f32_e32 v205, v77, v93
	v_max3_f32 v129, v129, v204, v205
	v_max_f32_e32 v204, v78, v94
	v_max_f32_e32 v205, v79, v95
	v_max3_f32 v129, v129, v204, v205
	v_max_f32_e32 v204, v80, v96
	v_max_f32_e32 v205, v81, v97
	v_max3_f32 v129, v129, v204, v205
	v_max_f32_e32 v204, v82, v98
	v_max_f32_e32 v206, v83, v83
	v_max_f32_e32 v205, v206, v99
	v_max3_f32 v129, v129, v204, v205
	v_and_b32_e32 v205, 64, v150
	v_xor_b32_e32 v204, 32, v150
	v_add_u32_e32 v205, 64, v205
	v_cmp_lt_i32_e32 vcc, v204, v205
	s_nop 1
	v_cndmask_b32_e32 v204, v150, v204, vcc
	v_lshlrev_b32_e32 v204, 2, v204
	ds_bpermute_b32 v204, v204, v129
	s_waitcnt lgkmcnt(0)
	v_max_f32_e32 v129, v129, v204
	v_add_f32_e32 v204, 0xc2200000, v201
	v_cmp_lt_f32_e32 vcc, v129, v204
	s_cmp_eq_u64 vcc, exec
	s_cbranch_scc1 .LBB0_1743
	v_max_f32_e32 v204, v201, v201
	v_max_f32_e32 v129, v204, v129
	v_cmp_gt_f32_e32 vcc, v129, v201
	s_cbranch_vccz .LBB0_1741
	v_sub_f32_e32 v201, v201, v129
	v_exp_f32_e32 v204, v201
	v_mov_b32_e32 v201, v129
	v_mul_f32_e32 v34, v34, v204
	v_pk_mul_f32 v[32:33], v[32:33], v[204:205] op_sel_hi:[1,0]
	v_pk_mul_f32 v[30:31], v[30:31], v[204:205] op_sel_hi:[1,0]
	v_pk_mul_f32 v[28:29], v[28:29], v[204:205] op_sel_hi:[1,0]
	v_pk_mul_f32 v[26:27], v[26:27], v[204:205] op_sel_hi:[1,0]
	v_pk_mul_f32 v[24:25], v[24:25], v[204:205] op_sel_hi:[1,0]
	v_pk_mul_f32 v[22:23], v[22:23], v[204:205] op_sel_hi:[1,0]
	v_pk_mul_f32 v[20:21], v[20:21], v[204:205] op_sel_hi:[1,0]
	v_pk_mul_f32 v[18:19], v[18:19], v[204:205] op_sel_hi:[1,0]
	v_pk_mul_f32 v[16:17], v[16:17], v[204:205] op_sel_hi:[1,0]
	v_pk_mul_f32 v[14:15], v[14:15], v[204:205] op_sel_hi:[1,0]
	v_pk_mul_f32 v[12:13], v[12:13], v[204:205] op_sel_hi:[1,0]
	v_pk_mul_f32 v[10:11], v[10:11], v[204:205] op_sel_hi:[1,0]
	v_pk_mul_f32 v[8:9], v[8:9], v[204:205] op_sel_hi:[1,0]
	v_pk_mul_f32 v[6:7], v[6:7], v[204:205] op_sel_hi:[1,0]
	v_pk_mul_f32 v[4:5], v[4:5], v[204:205] op_sel_hi:[1,0]
	v_pk_mul_f32 v[2:3], v[2:3], v[204:205] op_sel_hi:[1,0]
	s_branch .LBB0_1742

; __device__ __forceinline__ unsigned pk(float lo, float hi) { return pg8::cvt_pk_bf16(lo, hi); }
;     __device__ __forceinline__ void operator()(const pg8::f32x4 (&acc)[2][2][4][2], const pg8::Unit& u, int wr, int wc, int fr, int fq) const {
;         const int row0 = u.pm * 256 + wr * 64 + fr;
; #pragma unroll
;         for (int ai = 0; ai < 2; ++ai)
; #pragma unroll
;             for (int m = 0; m < 4; ++m) {
;                 const int row = row0 + ai * 128 + m * 16; const float rs = rsqrtf(ss[row] * (1.f / DM) + EPS);
;                 float y[8];
; #pragma unroll
;                 for (int n = 0; n < 2; ++n)
; #pragma unroll
;                     for (int i = 0; i < 4; ++i) { const float g = acc[ai][0][m][n][i] * rs, up = acc[ai][1][m][n][i] * rs; y[4 * n + i] = g * up * __builtin_amdgcn_rcpf(1.f + __expf(-g)); }
;                 u32x4 w; w.x = pk(y[0], y[1]); w.y = pk(y[2], y[3]); w.z = pk(y[4], y[5]); w.w = pk(y[6], y[7]);
;                 *(u32x4*)(act + (size_t)row * DFF + u.pn * 128 + wc * 32 + 8 * fq) = w;
;             }
.LBB0_1938:
	v_lshl_add_u32 v183, s26, 8, v152
	v_mov_b32_e32 v195, 0
	v_mov_b32_e32 v194, v183
	v_lshl_add_u64 v[194:195], v[194:195], 2, s[8:9]
	global_load_dword v148, v[194:195], off
	global_load_dword v150, v[194:195], off offset:64
	global_load_dword v158, v[194:195], off offset:128
	global_load_dword v160, v[194:195], off offset:192
	global_load_dword v162, v[194:195], off offset:512
	global_load_dword v164, v[194:195], off offset:576
	global_load_dword v166, v[194:195], off offset:640
	global_load_dword v184, v[194:195], off offset:704
	s_lshl_b32 s98, s27, 8
	v_mul_u32_u24_e32 v196, 0x1600, v183
	v_add3_u32 v196, v196, s98, v138
	v_add_u32_e32 v196, s4, v196
	v_mov_b32_e32 v190, 0xbfb8aa3b
	v_mov_b32_e32 v192, 1.0
	s_waitcnt vmcnt(0)
	v_fmamk_f32 v148, v148, 0x3a800000, v157
	v_fmamk_f32 v150, v150, 0x3a800000, v157
	v_fmamk_f32 v158, v158, 0x3a800000, v157
	v_fmamk_f32 v160, v160, 0x3a800000, v157
	v_fmamk_f32 v162, v162, 0x3a800000, v157
	v_fmamk_f32 v164, v164, 0x3a800000, v157
	v_fmamk_f32 v166, v166, 0x3a800000, v157
	v_fmamk_f32 v184, v184, 0x3a800000, v157
	v_mul_f32_e32 v198, 0x4b800000, v148
	v_cmp_gt_f32_e32 vcc, s54, v148
	s_nop 1
	v_cndmask_b32_e32 v148, v148, v198, vcc
	v_rsq_f32_e32 v148, v148
	s_nop 0
	v_mul_f32_e32 v198, 0x45800000, v148
	v_cndmask_b32_e32 v148, v148, v198, vcc
	v_mul_f32_e32 v198, 0x4b800000, v150
	v_cmp_gt_f32_e32 vcc, s54, v150
	s_nop 1
	v_cndmask_b32_e32 v150, v150, v198, vcc
	v_rsq_f32_e32 v150, v150
	s_nop 0
	v_mul_f32_e32 v198, 0x45800000, v150
	v_cndmask_b32_e32 v150, v150, v198, vcc
	v_mul_f32_e32 v198, 0x4b800000, v158
	v_cmp_gt_f32_e32 vcc, s54, v158
	s_nop 1
	v_cndmask_b32_e32 v158, v158, v198, vcc
	v_rsq_f32_e32 v158, v158
	s_nop 0
	v_mul_f32_e32 v198, 0x45800000, v158
	v_cndmask_b32_e32 v158, v158, v198, vcc
	v_mul_f32_e32 v198, 0x4b800000, v160
	v_cmp_gt_f32_e32 vcc, s54, v160
	s_nop 1
	v_cndmask_b32_e32 v160, v160, v198, vcc
	v_rsq_f32_e32 v160, v160
	s_nop 0
	v_mul_f32_e32 v198, 0x45800000, v160
	v_cndmask_b32_e32 v160, v160, v198, vcc
	v_mul_f32_e32 v198, 0x4b800000, v162
	v_cmp_gt_f32_e32 vcc, s54, v162
	s_nop 1
	v_cndmask_b32_e32 v162, v162, v198, vcc
	v_rsq_f32_e32 v162, v162
	s_nop 0
	v_mul_f32_e32 v198, 0x45800000, v162
	v_cndmask_b32_e32 v162, v162, v198, vcc
	v_mul_f32_e32 v198, 0x4b800000, v164
	v_cmp_gt_f32_e32 vcc, s54, v164
	s_nop 1
	v_cndmask_b32_e32 v164, v164, v198, vcc
	v_rsq_f32_e32 v164, v164
	s_nop 0
	v_mul_f32_e32 v198, 0x45800000, v164
	v_cndmask_b32_e32 v164, v164, v198, vcc
	v_mul_f32_e32 v198, 0x4b800000, v166
	v_cmp_gt_f32_e32 vcc, s54, v166
	s_nop 1
	v_cndmask_b32_e32 v166, v166, v198, vcc
	v_rsq_f32_e32 v166, v166
	s_nop 0
	v_mul_f32_e32 v198, 0x45800000, v166
	v_cndmask_b32_e32 v166, v166, v198, vcc
	v_mul_f32_e32 v198, 0x4b800000, v184
	v_cmp_gt_f32_e32 vcc, s54, v184
	s_nop 1
	v_cndmask_b32_e32 v184, v184, v198, vcc
	v_rsq_f32_e32 v184, v184
	s_nop 0
	v_mul_f32_e32 v198, 0x45800000, v184
	v_cndmask_b32_e32 v184, v184, v198, vcc
	v_pk_mul_f32 v[126:127], v[126:127], v[148:149] op_sel_hi:[1,0]
	v_pk_mul_f32 v[128:129], v[128:129], v[148:149] op_sel_hi:[1,0]
	v_pk_mul_f32 v[122:123], v[122:123], v[148:149] op_sel_hi:[1,0]
	v_pk_mul_f32 v[124:125], v[124:125], v[148:149] op_sel_hi:[1,0]
	v_pk_mul_f32 v[118:119], v[118:119], v[148:149] op_sel_hi:[1,0]
	v_pk_mul_f32 v[120:121], v[120:121], v[148:149] op_sel_hi:[1,0]
	v_pk_mul_f32 v[114:115], v[114:115], v[148:149] op_sel_hi:[1,0]
	v_pk_mul_f32 v[116:117], v[116:117], v[148:149] op_sel_hi:[1,0]
	v_pk_mul_f32 v[118:119], v[126:127], v[118:119]
	v_pk_mul_f32 v[120:121], v[128:129], v[120:121]
	v_pk_mul_f32 v[114:115], v[122:123], v[114:115]
	v_pk_mul_f32 v[116:117], v[124:125], v[116:117]
	v_pk_mul_f32 v[126:127], v[126:127], v[190:191] op_sel_hi:[1,0]
	v_pk_mul_f32 v[128:129], v[128:129], v[190:191] op_sel_hi:[1,0]
	v_pk_mul_f32 v[122:123], v[122:123], v[190:191] op_sel_hi:[1,0]
	v_pk_mul_f32 v[124:125], v[124:125], v[190:191] op_sel_hi:[1,0]
	v_exp_f32_e32 v126, v126
	v_exp_f32_e32 v127, v127
	v_exp_f32_e32 v128, v128
	v_exp_f32_e32 v129, v129
	v_exp_f32_e32 v122, v122
	v_exp_f32_e32 v123, v123
	v_exp_f32_e32 v124, v124
	v_exp_f32_e32 v125, v125
	v_pk_add_f32 v[126:127], v[126:127], v[192:193] op_sel_hi:[1,0]
	v_pk_add_f32 v[128:129], v[128:129], v[192:193] op_sel_hi:[1,0]
	v_pk_add_f32 v[122:123], v[122:123], v[192:193] op_sel_hi:[1,0]
	v_pk_add_f32 v[124:125], v[124:125], v[192:193] op_sel_hi:[1,0]
	v_rcp_f32_e32 v126, v126
	v_rcp_f32_e32 v127, v127
	v_rcp_f32_e32 v128, v128
	v_rcp_f32_e32 v129, v129
	v_rcp_f32_e32 v122, v122
	v_rcp_f32_e32 v123, v123
	v_rcp_f32_e32 v124, v124
	v_rcp_f32_e32 v125, v125
	v_pk_mul_f32 v[118:119], v[118:119], v[126:127]
	v_pk_mul_f32 v[120:121], v[120:121], v[128:129]
	v_pk_mul_f32 v[114:115], v[114:115], v[122:123]
	v_pk_mul_f32 v[116:117], v[116:117], v[124:125]
	v_cvt_pk_bf16_f32 v186, v118, v119
	v_cvt_pk_bf16_f32 v187, v120, v121
	v_cvt_pk_bf16_f32 v188, v114, v115
	v_cvt_pk_bf16_f32 v189, v116, v117
	global_store_dwordx4 v196, v[186:189], s[12:13]
	s_nop 1
	v_pk_mul_f32 v[110:111], v[110:111], v[150:151] op_sel_hi:[1,0]
	v_pk_mul_f32 v[112:113], v[112:113], v[150:151] op_sel_hi:[1,0]
	v_pk_mul_f32 v[106:107], v[106:107], v[150:151] op_sel_hi:[1,0]
	v_pk_mul_f32 v[108:109], v[108:109], v[150:151] op_sel_hi:[1,0]
	v_pk_mul_f32 v[102:103], v[102:103], v[150:151] op_sel_hi:[1,0]
	v_pk_mul_f32 v[104:105], v[104:105], v[150:151] op_sel_hi:[1,0]
	v_pk_mul_f32 v[98:99], v[98:99], v[150:151] op_sel_hi:[1,0]
	v_pk_mul_f32 v[100:101], v[100:101], v[150:151] op_sel_hi:[1,0]
	v_pk_mul_f32 v[102:103], v[110:111], v[102:103]
	v_pk_mul_f32 v[104:105], v[112:113], v[104:105]
; __device__ __forceinline__ unsigned pk(float lo, float hi) { return pg8::cvt_pk_bf16(lo, hi); }
;     __device__ __forceinline__ void operator()(const pg8::f32x4 (&acc)[2][2][4][2], const pg8::Unit& u, int wr, int wc, int fr, int fq) const {
;     ...
;             for (int m = 0; m < 4; ++m) {
;                 const int row = row0 + ai * 128 + m * 16; const float rs = rsqrtf(ss[row] * (1.f / DM) + EPS);
;                 float y[8];
; #pragma unroll
;                 for (int n = 0; n < 2; ++n)
; #pragma unroll
;                     for (int i = 0; i < 4; ++i) { const float g = acc[ai][0][m][n][i] * rs, up = acc[ai][1][m][n][i] * rs; y[4 * n + i] = g * up * __builtin_amdgcn_rcpf(1.f + __expf(-g)); }
;                 u32x4 w; w.x = pk(y[0], y[1]); w.y = pk(y[2], y[3]); w.z = pk(y[4], y[5]); w.w = pk(y[6], y[7]);
;                 *(u32x4*)(act + (size_t)row * DFF + u.pn * 128 + wc * 32 + 8 * fq) = w;
;             }
	v_pk_mul_f32 v[98:99], v[106:107], v[98:99]
	v_pk_mul_f32 v[100:101], v[108:109], v[100:101]
	v_pk_mul_f32 v[110:111], v[110:111], v[190:191] op_sel_hi:[1,0]
	v_pk_mul_f32 v[112:113], v[112:113], v[190:191] op_sel_hi:[1,0]
	v_pk_mul_f32 v[106:107], v[106:107], v[190:191] op_sel_hi:[1,0]
	v_pk_mul_f32 v[108:109], v[108:109], v[190:191] op_sel_hi:[1,0]
	v_exp_f32_e32 v110, v110
	v_exp_f32_e32 v111, v111
	v_exp_f32_e32 v112, v112
	v_exp_f32_e32 v113, v113
	v_exp_f32_e32 v106, v106
	v_exp_f32_e32 v107, v107
	v_exp_f32_e32 v108, v108
	v_exp_f32_e32 v109, v109
	v_pk_add_f32 v[110:111], v[110:111], v[192:193] op_sel_hi:[1,0]
	v_pk_add_f32 v[112:113], v[112:113], v[192:193] op_sel_hi:[1,0]
	v_pk_add_f32 v[106:107], v[106:107], v[192:193] op_sel_hi:[1,0]
	v_pk_add_f32 v[108:109], v[108:109], v[192:193] op_sel_hi:[1,0]
	v_rcp_f32_e32 v110, v110
	v_rcp_f32_e32 v111, v111
	v_rcp_f32_e32 v112, v112
	v_rcp_f32_e32 v113, v113
	v_rcp_f32_e32 v106, v106
	v_rcp_f32_e32 v107, v107
	v_rcp_f32_e32 v108, v108
	v_rcp_f32_e32 v109, v109
	v_pk_mul_f32 v[102:103], v[102:103], v[110:111]
	v_pk_mul_f32 v[104:105], v[104:105], v[112:113]
	v_pk_mul_f32 v[98:99], v[98:99], v[106:107]
	v_pk_mul_f32 v[100:101], v[100:101], v[108:109]
	v_cvt_pk_bf16_f32 v186, v102, v103
	v_cvt_pk_bf16_f32 v187, v104, v105
	v_cvt_pk_bf16_f32 v188, v98, v99
	v_cvt_pk_bf16_f32 v189, v100, v101
	v_add_u32_e32 v197, 0x16000, v196
	global_store_dwordx4 v197, v[186:189], s[12:13]
	s_nop 1
	v_pk_mul_f32 v[94:95], v[94:95], v[158:159] op_sel_hi:[1,0]
	v_pk_mul_f32 v[96:97], v[96:97], v[158:159] op_sel_hi:[1,0]
	v_pk_mul_f32 v[90:91], v[90:91], v[158:159] op_sel_hi:[1,0]
	v_pk_mul_f32 v[92:93], v[92:93], v[158:159] op_sel_hi:[1,0]
	v_pk_mul_f32 v[86:87], v[86:87], v[158:159] op_sel_hi:[1,0]
	v_pk_mul_f32 v[88:89], v[88:89], v[158:159] op_sel_hi:[1,0]
	v_pk_mul_f32 v[82:83], v[82:83], v[158:159] op_sel_hi:[1,0]
	v_pk_mul_f32 v[84:85], v[84:85], v[158:159] op_sel_hi:[1,0]
	v_pk_mul_f32 v[86:87], v[94:95], v[86:87]
	v_pk_mul_f32 v[88:89], v[96:97], v[88:89]
	v_pk_mul_f32 v[82:83], v[90:91], v[82:83]
	v_pk_mul_f32 v[84:85], v[92:93], v[84:85]
	v_pk_mul_f32 v[94:95], v[94:95], v[190:191] op_sel_hi:[1,0]
	v_pk_mul_f32 v[96:97], v[96:97], v[190:191] op_sel_hi:[1,0]
	v_pk_mul_f32 v[90:91], v[90:91], v[190:191] op_sel_hi:[1,0]
	v_pk_mul_f32 v[92:93], v[92:93], v[190:191] op_sel_hi:[1,0]
	v_exp_f32_e32 v94, v94
	v_exp_f32_e32 v95, v95
	v_exp_f32_e32 v96, v96
	v_exp_f32_e32 v97, v97
	v_exp_f32_e32 v90, v90
	v_exp_f32_e32 v91, v91
	v_exp_f32_e32 v92, v92
	v_exp_f32_e32 v93, v93
	v_pk_add_f32 v[94:95], v[94:95], v[192:193] op_sel_hi:[1,0]
	v_pk_add_f32 v[96:97], v[96:97], v[192:193] op_sel_hi:[1,0]
	v_pk_add_f32 v[90:91], v[90:91], v[192:193] op_sel_hi:[1,0]
	v_pk_add_f32 v[92:93], v[92:93], v[192:193] op_sel_hi:[1,0]
	v_rcp_f32_e32 v94, v94
	v_rcp_f32_e32 v95, v95
	v_rcp_f32_e32 v96, v96
	v_rcp_f32_e32 v97, v97
	v_rcp_f32_e32 v90, v90
	v_rcp_f32_e32 v91, v91
	v_rcp_f32_e32 v92, v92
	v_rcp_f32_e32 v93, v93
	v_pk_mul_f32 v[86:87], v[86:87], v[94:95]
	v_pk_mul_f32 v[88:89], v[88:89], v[96:97]
	v_pk_mul_f32 v[82:83], v[82:83], v[90:91]
	v_pk_mul_f32 v[84:85], v[84:85], v[92:93]
	v_cvt_pk_bf16_f32 v186, v86, v87
	v_cvt_pk_bf16_f32 v187, v88, v89
	v_cvt_pk_bf16_f32 v188, v82, v83
	v_cvt_pk_bf16_f32 v189, v84, v85
	v_add_u32_e32 v197, 0x2c000, v196
	global_store_dwordx4 v197, v[186:189], s[12:13]
	s_nop 1
	v_pk_mul_f32 v[78:79], v[78:79], v[160:161] op_sel_hi:[1,0]
	v_pk_mul_f32 v[80:81], v[80:81], v[160:161] op_sel_hi:[1,0]
	v_pk_mul_f32 v[74:75], v[74:75], v[160:161] op_sel_hi:[1,0]
	v_pk_mul_f32 v[76:77], v[76:77], v[160:161] op_sel_hi:[1,0]
	v_pk_mul_f32 v[70:71], v[70:71], v[160:161] op_sel_hi:[1,0]
	v_pk_mul_f32 v[72:73], v[72:73], v[160:161] op_sel_hi:[1,0]
	v_pk_mul_f32 v[66:67], v[66:67], v[160:161] op_sel_hi:[1,0]
	v_pk_mul_f32 v[68:69], v[68:69], v[160:161] op_sel_hi:[1,0]
	v_pk_mul_f32 v[70:71], v[78:79], v[70:71]
	v_pk_mul_f32 v[72:73], v[80:81], v[72:73]
	v_pk_mul_f32 v[66:67], v[74:75], v[66:67]
	v_pk_mul_f32 v[68:69], v[76:77], v[68:69]
	v_pk_mul_f32 v[78:79], v[78:79], v[190:191] op_sel_hi:[1,0]
	v_pk_mul_f32 v[80:81], v[80:81], v[190:191] op_sel_hi:[1,0]
	v_pk_mul_f32 v[74:75], v[74:75], v[190:191] op_sel_hi:[1,0]
	v_pk_mul_f32 v[76:77], v[76:77], v[190:191] op_sel_hi:[1,0]
	v_exp_f32_e32 v78, v78
	v_exp_f32_e32 v79, v79
	v_exp_f32_e32 v80, v80
	v_exp_f32_e32 v81, v81
	v_exp_f32_e32 v74, v74
	v_exp_f32_e32 v75, v75
	v_exp_f32_e32 v76, v76
	v_exp_f32_e32 v77, v77
	v_pk_add_f32 v[78:79], v[78:79], v[192:193] op_sel_hi:[1,0]
	v_pk_add_f32 v[80:81], v[80:81], v[192:193] op_sel_hi:[1,0]
	v_pk_add_f32 v[74:75], v[74:75], v[192:193] op_sel_hi:[1,0]
	v_pk_add_f32 v[76:77], v[76:77], v[192:193] op_sel_hi:[1,0]
	v_rcp_f32_e32 v78, v78
	v_rcp_f32_e32 v79, v79
	v_rcp_f32_e32 v80, v80
	v_rcp_f32_e32 v81, v81
	v_rcp_f32_e32 v74, v74
	v_rcp_f32_e32 v75, v75
	v_rcp_f32_e32 v76, v76
	v_rcp_f32_e32 v77, v77
	v_pk_mul_f32 v[70:71], v[70:71], v[78:79]
	v_pk_mul_f32 v[72:73], v[72:73], v[80:81]
	v_pk_mul_f32 v[66:67], v[66:67], v[74:75]
	v_pk_mul_f32 v[68:69], v[68:69], v[76:77]
	v_cvt_pk_bf16_f32 v186, v70, v71
	v_cvt_pk_bf16_f32 v187, v72, v73
	v_cvt_pk_bf16_f32 v188, v66, v67
	v_cvt_pk_bf16_f32 v189, v68, v69
	v_add_u32_e32 v197, 0x42000, v196
	global_store_dwordx4 v197, v[186:189], s[12:13]
	s_nop 1
	v_pk_mul_f32 v[62:63], v[62:63], v[162:163] op_sel_hi:[1,0]
	v_pk_mul_f32 v[64:65], v[64:65], v[162:163] op_sel_hi:[1,0]
	v_pk_mul_f32 v[58:59], v[58:59], v[162:163] op_sel_hi:[1,0]
	v_pk_mul_f32 v[60:61], v[60:61], v[162:163] op_sel_hi:[1,0]
	v_pk_mul_f32 v[54:55], v[54:55], v[162:163] op_sel_hi:[1,0]
; __device__ __forceinline__ unsigned pk(float lo, float hi) { return pg8::cvt_pk_bf16(lo, hi); }
;     __device__ __forceinline__ void operator()(const pg8::f32x4 (&acc)[2][2][4][2], const pg8::Unit& u, int wr, int wc, int fr, int fq) const {
;     ...
;             for (int m = 0; m < 4; ++m) {
;                 const int row = row0 + ai * 128 + m * 16; const float rs = rsqrtf(ss[row] * (1.f / DM) + EPS);
;                 float y[8];
; #pragma unroll
;                 for (int n = 0; n < 2; ++n)
; #pragma unroll
;                     for (int i = 0; i < 4; ++i) { const float g = acc[ai][0][m][n][i] * rs, up = acc[ai][1][m][n][i] * rs; y[4 * n + i] = g * up * __builtin_amdgcn_rcpf(1.f + __expf(-g)); }
;                 u32x4 w; w.x = pk(y[0], y[1]); w.y = pk(y[2], y[3]); w.z = pk(y[4], y[5]); w.w = pk(y[6], y[7]);
;                 *(u32x4*)(act + (size_t)row * DFF + u.pn * 128 + wc * 32 + 8 * fq) = w;
;             }
	v_pk_mul_f32 v[56:57], v[56:57], v[162:163] op_sel_hi:[1,0]
	v_pk_mul_f32 v[50:51], v[50:51], v[162:163] op_sel_hi:[1,0]
	v_pk_mul_f32 v[52:53], v[52:53], v[162:163] op_sel_hi:[1,0]
	v_pk_mul_f32 v[54:55], v[62:63], v[54:55]
	v_pk_mul_f32 v[56:57], v[64:65], v[56:57]
	v_pk_mul_f32 v[50:51], v[58:59], v[50:51]
	v_pk_mul_f32 v[52:53], v[60:61], v[52:53]
	v_pk_mul_f32 v[62:63], v[62:63], v[190:191] op_sel_hi:[1,0]
	v_pk_mul_f32 v[64:65], v[64:65], v[190:191] op_sel_hi:[1,0]
	v_pk_mul_f32 v[58:59], v[58:59], v[190:191] op_sel_hi:[1,0]
	v_pk_mul_f32 v[60:61], v[60:61], v[190:191] op_sel_hi:[1,0]
	v_exp_f32_e32 v62, v62
	v_exp_f32_e32 v63, v63
	v_exp_f32_e32 v64, v64
	v_exp_f32_e32 v65, v65
	v_exp_f32_e32 v58, v58
	v_exp_f32_e32 v59, v59
	v_exp_f32_e32 v60, v60
	v_exp_f32_e32 v61, v61
	v_pk_add_f32 v[62:63], v[62:63], v[192:193] op_sel_hi:[1,0]
	v_pk_add_f32 v[64:65], v[64:65], v[192:193] op_sel_hi:[1,0]
	v_pk_add_f32 v[58:59], v[58:59], v[192:193] op_sel_hi:[1,0]
	v_pk_add_f32 v[60:61], v[60:61], v[192:193] op_sel_hi:[1,0]
	v_rcp_f32_e32 v62, v62
	v_rcp_f32_e32 v63, v63
	v_rcp_f32_e32 v64, v64
	v_rcp_f32_e32 v65, v65
	v_rcp_f32_e32 v58, v58
	v_rcp_f32_e32 v59, v59
	v_rcp_f32_e32 v60, v60
	v_rcp_f32_e32 v61, v61
	v_pk_mul_f32 v[54:55], v[54:55], v[62:63]
	v_pk_mul_f32 v[56:57], v[56:57], v[64:65]
	v_pk_mul_f32 v[50:51], v[50:51], v[58:59]
	v_pk_mul_f32 v[52:53], v[52:53], v[60:61]
	v_cvt_pk_bf16_f32 v186, v54, v55
	v_cvt_pk_bf16_f32 v187, v56, v57
	v_cvt_pk_bf16_f32 v188, v50, v51
	v_cvt_pk_bf16_f32 v189, v52, v53
	v_add_u32_e32 v197, 0xb0000, v196
	global_store_dwordx4 v197, v[186:189], s[12:13]
	s_nop 1
	v_pk_mul_f32 v[46:47], v[46:47], v[164:165] op_sel_hi:[1,0]
	v_pk_mul_f32 v[48:49], v[48:49], v[164:165] op_sel_hi:[1,0]
	v_pk_mul_f32 v[42:43], v[42:43], v[164:165] op_sel_hi:[1,0]
	v_pk_mul_f32 v[44:45], v[44:45], v[164:165] op_sel_hi:[1,0]
	v_pk_mul_f32 v[38:39], v[38:39], v[164:165] op_sel_hi:[1,0]
	v_pk_mul_f32 v[40:41], v[40:41], v[164:165] op_sel_hi:[1,0]
	v_pk_mul_f32 v[34:35], v[34:35], v[164:165] op_sel_hi:[1,0]
	v_pk_mul_f32 v[36:37], v[36:37], v[164:165] op_sel_hi:[1,0]
	v_pk_mul_f32 v[38:39], v[46:47], v[38:39]
	v_pk_mul_f32 v[40:41], v[48:49], v[40:41]
	v_pk_mul_f32 v[34:35], v[42:43], v[34:35]
	v_pk_mul_f32 v[36:37], v[44:45], v[36:37]
	v_pk_mul_f32 v[46:47], v[46:47], v[190:191] op_sel_hi:[1,0]
	v_pk_mul_f32 v[48:49], v[48:49], v[190:191] op_sel_hi:[1,0]
	v_pk_mul_f32 v[42:43], v[42:43], v[190:191] op_sel_hi:[1,0]
	v_pk_mul_f32 v[44:45], v[44:45], v[190:191] op_sel_hi:[1,0]
	v_exp_f32_e32 v46, v46
	v_exp_f32_e32 v47, v47
	v_exp_f32_e32 v48, v48
	v_exp_f32_e32 v49, v49
	v_exp_f32_e32 v42, v42
	v_exp_f32_e32 v43, v43
	v_exp_f32_e32 v44, v44
	v_exp_f32_e32 v45, v45
	v_pk_add_f32 v[46:47], v[46:47], v[192:193] op_sel_hi:[1,0]
	v_pk_add_f32 v[48:49], v[48:49], v[192:193] op_sel_hi:[1,0]
	v_pk_add_f32 v[42:43], v[42:43], v[192:193] op_sel_hi:[1,0]
	v_pk_add_f32 v[44:45], v[44:45], v[192:193] op_sel_hi:[1,0]
	v_rcp_f32_e32 v46, v46
	v_rcp_f32_e32 v47, v47
	v_rcp_f32_e32 v48, v48
	v_rcp_f32_e32 v49, v49
	v_rcp_f32_e32 v42, v42
	v_rcp_f32_e32 v43, v43
	v_rcp_f32_e32 v44, v44
	v_rcp_f32_e32 v45, v45
	v_pk_mul_f32 v[38:39], v[38:39], v[46:47]
	v_pk_mul_f32 v[40:41], v[40:41], v[48:49]
	v_pk_mul_f32 v[34:35], v[34:35], v[42:43]
	v_pk_mul_f32 v[36:37], v[36:37], v[44:45]
	v_cvt_pk_bf16_f32 v186, v38, v39
	v_cvt_pk_bf16_f32 v187, v40, v41
	v_cvt_pk_bf16_f32 v188, v34, v35
	v_cvt_pk_bf16_f32 v189, v36, v37
	v_add_u32_e32 v197, 0xc6000, v196
	global_store_dwordx4 v197, v[186:189], s[12:13]
	s_nop 1
	v_pk_mul_f32 v[30:31], v[30:31], v[166:167] op_sel_hi:[1,0]
	v_pk_mul_f32 v[32:33], v[32:33], v[166:167] op_sel_hi:[1,0]
	v_pk_mul_f32 v[26:27], v[26:27], v[166:167] op_sel_hi:[1,0]
; #define PG8_BAR __builtin_amdgcn_s_barrier()
; __device__ __forceinline__ unsigned pk(float lo, float hi) { return pg8::cvt_pk_bf16(lo, hi); }
; template <class Epi, class Sched, bool ALIGN_EPI = false, bool SP2 = false>
; __device__ __forceinline__ void gemm_phase(PG8_LAS unsigned char* lds, const Gemm g, const Sched& S, const Epi& E) {
;     ...
;         if (!has_next) break;
; #pragma unroll
;         for (int a = 0; a < 2; ++a)
; #pragma unroll
;             for (int b = 0; b < 2; ++b)
; #pragma unroll
;                 for (int m = 0; m < 4; ++m)
; #pragma unroll
;                     for (int n = 0; n < 2; ++n) acc[a][b][m][n] = (f32x4){0.f, 0.f, 0.f, 0.f};
;         cur = nxt; cA = nA; cB = nB; ++ui;
;         if constexpr (ALIGN_EPI) { if (wr == 1) PG8_BAR; }
;     __device__ __forceinline__ void operator()(const pg8::f32x4 (&acc)[2][2][4][2], const pg8::Unit& u, int wr, int wc, int fr, int fq) const {
;     ...
;             for (int m = 0; m < 4; ++m) {
;                 const int row = row0 + ai * 128 + m * 16; const float rs = rsqrtf(ss[row] * (1.f / DM) + EPS);
;                 float y[8];
; #pragma unroll
;                 for (int n = 0; n < 2; ++n)
; #pragma unroll
;                     for (int i = 0; i < 4; ++i) { const float g = acc[ai][0][m][n][i] * rs, up = acc[ai][1][m][n][i] * rs; y[4 * n + i] = g * up * __builtin_amdgcn_rcpf(1.f + __expf(-g)); }
;                 u32x4 w; w.x = pk(y[0], y[1]); w.y = pk(y[2], y[3]); w.z = pk(y[4], y[5]); w.w = pk(y[6], y[7]);
;                 *(u32x4*)(act + (size_t)row * DFF + u.pn * 128 + wc * 32 + 8 * fq) = w;
;             }
	v_pk_mul_f32 v[28:29], v[28:29], v[166:167] op_sel_hi:[1,0]
	v_pk_mul_f32 v[22:23], v[22:23], v[166:167] op_sel_hi:[1,0]
	v_pk_mul_f32 v[24:25], v[24:25], v[166:167] op_sel_hi:[1,0]
	v_pk_mul_f32 v[18:19], v[18:19], v[166:167] op_sel_hi:[1,0]
	v_pk_mul_f32 v[20:21], v[20:21], v[166:167] op_sel_hi:[1,0]
	v_pk_mul_f32 v[22:23], v[30:31], v[22:23]
	v_pk_mul_f32 v[24:25], v[32:33], v[24:25]
	v_pk_mul_f32 v[18:19], v[26:27], v[18:19]
	v_pk_mul_f32 v[20:21], v[28:29], v[20:21]
	v_pk_mul_f32 v[30:31], v[30:31], v[190:191] op_sel_hi:[1,0]
	v_pk_mul_f32 v[32:33], v[32:33], v[190:191] op_sel_hi:[1,0]
	v_pk_mul_f32 v[26:27], v[26:27], v[190:191] op_sel_hi:[1,0]
	v_pk_mul_f32 v[28:29], v[28:29], v[190:191] op_sel_hi:[1,0]
	v_exp_f32_e32 v30, v30
	v_exp_f32_e32 v31, v31
	v_exp_f32_e32 v32, v32
	v_exp_f32_e32 v33, v33
	v_exp_f32_e32 v26, v26
	v_exp_f32_e32 v27, v27
	v_exp_f32_e32 v28, v28
	v_exp_f32_e32 v29, v29
	v_pk_add_f32 v[30:31], v[30:31], v[192:193] op_sel_hi:[1,0]
	v_pk_add_f32 v[32:33], v[32:33], v[192:193] op_sel_hi:[1,0]
	v_pk_add_f32 v[26:27], v[26:27], v[192:193] op_sel_hi:[1,0]
	v_pk_add_f32 v[28:29], v[28:29], v[192:193] op_sel_hi:[1,0]
	v_rcp_f32_e32 v30, v30
	v_rcp_f32_e32 v31, v31
	v_rcp_f32_e32 v32, v32
	v_rcp_f32_e32 v33, v33
	v_rcp_f32_e32 v26, v26
	v_rcp_f32_e32 v27, v27
	v_rcp_f32_e32 v28, v28
	v_rcp_f32_e32 v29, v29
	v_pk_mul_f32 v[22:23], v[22:23], v[30:31]
	v_pk_mul_f32 v[24:25], v[24:25], v[32:33]
	v_pk_mul_f32 v[18:19], v[18:19], v[26:27]
	v_pk_mul_f32 v[20:21], v[20:21], v[28:29]
	v_cvt_pk_bf16_f32 v186, v22, v23
	v_cvt_pk_bf16_f32 v187, v24, v25
	v_cvt_pk_bf16_f32 v188, v18, v19
	v_cvt_pk_bf16_f32 v189, v20, v21
	v_add_u32_e32 v197, 0xdc000, v196
	global_store_dwordx4 v197, v[186:189], s[12:13]
	s_nop 1
	v_pk_mul_f32 v[14:15], v[14:15], v[184:185] op_sel_hi:[1,0]
	v_pk_mul_f32 v[16:17], v[16:17], v[184:185] op_sel_hi:[1,0]
	v_pk_mul_f32 v[10:11], v[10:11], v[184:185] op_sel_hi:[1,0]
	v_pk_mul_f32 v[12:13], v[12:13], v[184:185] op_sel_hi:[1,0]
	v_pk_mul_f32 v[6:7], v[6:7], v[184:185] op_sel_hi:[1,0]
	v_pk_mul_f32 v[8:9], v[8:9], v[184:185] op_sel_hi:[1,0]
	v_pk_mul_f32 v[2:3], v[2:3], v[184:185] op_sel_hi:[1,0]
	v_pk_mul_f32 v[4:5], v[4:5], v[184:185] op_sel_hi:[1,0]
	v_pk_mul_f32 v[6:7], v[14:15], v[6:7]
	v_pk_mul_f32 v[8:9], v[16:17], v[8:9]
	v_pk_mul_f32 v[2:3], v[10:11], v[2:3]
	v_pk_mul_f32 v[4:5], v[12:13], v[4:5]
	v_pk_mul_f32 v[14:15], v[14:15], v[190:191] op_sel_hi:[1,0]
	v_pk_mul_f32 v[16:17], v[16:17], v[190:191] op_sel_hi:[1,0]
	v_pk_mul_f32 v[10:11], v[10:11], v[190:191] op_sel_hi:[1,0]
	v_pk_mul_f32 v[12:13], v[12:13], v[190:191] op_sel_hi:[1,0]
	v_exp_f32_e32 v14, v14
	v_exp_f32_e32 v15, v15
	v_exp_f32_e32 v16, v16
	v_exp_f32_e32 v17, v17
	v_exp_f32_e32 v10, v10
	v_exp_f32_e32 v11, v11
	v_exp_f32_e32 v12, v12
	v_exp_f32_e32 v13, v13
	v_pk_add_f32 v[14:15], v[14:15], v[192:193] op_sel_hi:[1,0]
	v_pk_add_f32 v[16:17], v[16:17], v[192:193] op_sel_hi:[1,0]
	v_pk_add_f32 v[10:11], v[10:11], v[192:193] op_sel_hi:[1,0]
	v_pk_add_f32 v[12:13], v[12:13], v[192:193] op_sel_hi:[1,0]
	v_rcp_f32_e32 v14, v14
	v_rcp_f32_e32 v15, v15
	v_rcp_f32_e32 v16, v16
	v_rcp_f32_e32 v17, v17
	v_rcp_f32_e32 v10, v10
	v_rcp_f32_e32 v11, v11
	v_rcp_f32_e32 v12, v12
	v_rcp_f32_e32 v13, v13
	v_pk_mul_f32 v[6:7], v[6:7], v[14:15]
	v_pk_mul_f32 v[8:9], v[8:9], v[16:17]
	v_pk_mul_f32 v[2:3], v[2:3], v[10:11]
	v_pk_mul_f32 v[4:5], v[4:5], v[12:13]
	v_cvt_pk_bf16_f32 v186, v6, v7
	v_cvt_pk_bf16_f32 v187, v8, v9
	v_cvt_pk_bf16_f32 v188, v2, v3
	v_cvt_pk_bf16_f32 v189, v4, v5
	v_add_u32_e32 v197, 0xf2000, v196
	global_store_dwordx4 v197, v[186:189], s[12:13]
	s_nop 1
	s_andn2_b64 vcc, exec, s[0:1]
	s_mov_b64 s[0:1], -1
	s_cbranch_vccnz .LBB0_1931
	s_andn2_b64 vcc, exec, s[6:7]
	s_cbranch_vccnz .LBB0_1930
	s_barrier
	s_branch .LBB0_1930

; __global__ void __launch_bounds__(512, 2) fwd(Args a) {
	.amdhsa_kernel _Z3fwd4Args
		.amdhsa_group_segment_fixed_size 0
		.amdhsa_private_segment_fixed_size 0
		.amdhsa_kernarg_size 432
		.amdhsa_user_sgpr_count 2
		.amdhsa_user_sgpr_dispatch_ptr 0
		.amdhsa_user_sgpr_queue_ptr 0
		.amdhsa_user_sgpr_kernarg_segment_ptr 1
		.amdhsa_user_sgpr_dispatch_id 0
		.amdhsa_user_sgpr_kernarg_preload_length 0
		.amdhsa_user_sgpr_kernarg_preload_offset 0
		.amdhsa_user_sgpr_private_segment_size 0
		.amdhsa_uses_dynamic_stack 0
		.amdhsa_enable_private_segment 0
		.amdhsa_system_sgpr_workgroup_id_x 1
		.amdhsa_system_sgpr_workgroup_id_y 0
		.amdhsa_system_sgpr_workgroup_id_z 0
		.amdhsa_system_sgpr_workgroup_info 0
		.amdhsa_system_vgpr_workitem_id 0
		.amdhsa_next_free_vgpr 253
		.amdhsa_next_free_sgpr 102
		.amdhsa_accum_offset 256
		.amdhsa_reserve_vcc 1
		.amdhsa_float_round_mode_32 0
		.amdhsa_float_round_mode_16_64 0
		.amdhsa_float_denorm_mode_32 3
		.amdhsa_float_denorm_mode_16_64 3
		.amdhsa_dx10_clamp 1
		.amdhsa_ieee_mode 1
		.amdhsa_fp16_overflow 0
		.amdhsa_tg_split 0
		.amdhsa_exception_fp_ieee_invalid_op 0
		.amdhsa_exception_fp_denorm_src 0
		.amdhsa_exception_fp_ieee_div_zero 0
		.amdhsa_exception_fp_ieee_overflow 0
		.amdhsa_exception_fp_ieee_underflow 0
		.amdhsa_exception_fp_ieee_inexact 0
		.amdhsa_exception_int_div_zero 0
	.end_amdhsa_kernel

; __global__ void __launch_bounds__(512, 2) fwd(Args a) {
amdhsa.kernels:
  - .agpr_count:     0
    .args:
      - .offset:         0
        .size:           176
        .value_kind:     by_value
      - .offset:         176
        .size:           4
        .value_kind:     hidden_block_count_x
      - .offset:         180
        .size:           4
        .value_kind:     hidden_block_count_y
      - .offset:         184
        .size:           4
        .value_kind:     hidden_block_count_z
      - .offset:         188
        .size:           2
        .value_kind:     hidden_group_size_x
      - .offset:         190
        .size:           2
        .value_kind:     hidden_group_size_y
      - .offset:         192
        .size:           2
        .value_kind:     hidden_group_size_z
      - .offset:         194
        .size:           2
        .value_kind:     hidden_remainder_x
      - .offset:         196
        .size:           2
        .value_kind:     hidden_remainder_y
      - .offset:         198
        .size:           2
        .value_kind:     hidden_remainder_z
      - .offset:         216
        .size:           8
        .value_kind:     hidden_global_offset_x
      - .offset:         224
        .size:           8
        .value_kind:     hidden_global_offset_y
      - .offset:         232
        .size:           8
        .value_kind:     hidden_global_offset_z
      - .offset:         240
        .size:           2
        .value_kind:     hidden_grid_dims
      - .offset:         296
        .size:           4
        .value_kind:     hidden_dynamic_lds_size
    .group_segment_fixed_size: 0
    .kernarg_segment_align: 8
    .kernarg_segment_size: 432
    .language:       OpenCL C
    .language_version:
      - 2
      - 0
    .max_flat_workgroup_size: 512
    .name:           _Z3fwd4Args
    .private_segment_fixed_size: 0
    .sgpr_count:     108
    .sgpr_spill_count: 20
    .symbol:         _Z3fwd4Args.kd
    .uniform_work_group_size: 1
    .uses_dynamic_stack: false
    .vgpr_count:     253
    .vgpr_spill_count: 0
    .wavefront_size: 64
